# P4 conv+gate: n=0 and n=1 column quads merged into one 16-byte store per row group (8 dwordx4 instead of 16 dwordx2 stores per wave and tile)
# speedup vs baseline: 1.0392x; 1.0073x over previous
; #define LAS __attribute__((address_space(3)))
;     template <bool BND> __device__ __forceinline__ void conv_gate(f32x4 (&acc)[2][2][4][2], const Unit& u, int wr, int wc, int fr, int fq, int tok0, int pcol) const {
;     ...
;             for (int bj = 0; bj < 2; ++bj) { const int c = bj * DFF + fcol + 4 * n;
;                 w0[bj] = *(const f32x4*)(convw + c); w1[bj] = *(const f32x4*)(convw + 2 * DFF + c); w2[bj] = *(const f32x4*)(convw + 4 * DFF + c); bb[bj] = *(const f32x4*)(convb + c); }
; #pragma unroll
;             for (int ai = 0; ai < 2; ++ai) {
;                 const int blk = 2 * ai + wr;
;                 f32x4 pe[2], ne[2];
; #pragma unroll
;                 for (int bj = 0; bj < 2; ++bj) {
;                     pe[bj] = blk > 0 ? *(const LAS f32x4*)(edge + ((blk - 1) * 2 + 1) * 256 + 128 * bj + pcol + 4 * n) : (f32x4){0.f, 0.f, 0.f, 0.f};
;                     ne[bj] = blk < 3 ? *(const LAS f32x4*)(edge + ((blk + 1) * 2 + 0) * 256 + 128 * bj + pcol + 4 * n) : (f32x4){0.f, 0.f, 0.f, 0.f};
;                 }
; #pragma unroll
;                 for (int m = 0; m < 4; ++m) {
;                     const int r = ai * 128 + wr * 64 + m * 16 + fr, tok = tok0 + r;
;                     bool isfirst = false, islast = false;
;                     if (BND) { const int S1 = (tok < NPROMPT ? SEQP : SEQS) - 1, pos = tok & S1; isfirst = pos == 0; islast = pos == S1; }
;                     f32x4 cv[2];
; #pragma unroll
;                     for (int bj = 0; bj < 2; ++bj) {
;                         const f32x4 cur = acc[ai][bj][m][n];
;                         const f32x4 ups = m > 0 ? acc[ai][bj][m > 0 ? m - 1 : 0][n] : pe[bj];
;                         const f32x4 dns = m < 3 ? acc[ai][bj][m < 3 ? m + 1 : 3][n] : ne[bj];
;                         f32x4 prev, next;
; #pragma unroll
;                         for (int j = 0; j < 4; ++j) {
;                             const float t1 = fr == 15 ? ups[j] : cur[j]; float pv = dpp_ror1(t1);
;                             const float t2 = fr == 0 ? dns[j] : cur[j]; float nx = dpp_ror15(t2);
;                             if (BND) { prev[j] = isfirst ? 0.f : pv; next[j] = islast ? 0.f : nx; } else { prev[j] = pv; next[j] = nx; }
;                         }
;                         cv[bj] = w0[bj] * prev + w1[bj] * cur + w2[bj] * next + bb[bj];
;                     }
;                     f32x4 a;
; #pragma unroll
.Lconv_keep_1:
	v_cndmask_b32_e64 v100, v32, v132, s[8:9]
	v_cndmask_b32_e64 v101, v33, v133, s[8:9]
	v_cndmask_b32_e64 v102, v34, v134, s[8:9]
	v_cndmask_b32_e64 v103, v35, v135, s[8:9]
	v_cndmask_b32_e64 v104, v36, v136, s[8:9]
	v_cndmask_b32_e64 v105, v37, v137, s[8:9]
	v_cndmask_b32_e64 v106, v38, v138, s[8:9]
	v_cndmask_b32_e64 v107, v39, v139, s[8:9]
	v_cndmask_b32_e64 v108, v32, v194, s[6:7]
	v_cndmask_b32_e64 v109, v33, v195, s[6:7]
	v_cndmask_b32_e64 v110, v34, v192, s[6:7]
	v_cndmask_b32_e64 v111, v35, v193, s[6:7]
	v_cndmask_b32_e64 v112, v36, v198, s[6:7]
	v_cndmask_b32_e64 v113, v37, v199, s[6:7]
	v_cndmask_b32_e64 v114, v38, v196, s[6:7]
	v_cndmask_b32_e64 v115, v39, v197, s[6:7]
	v_fma_f32 v116, v76, v32, v64
	v_fma_f32 v117, v77, v33, v65
	v_fma_f32 v118, v78, v34, v66
	v_fma_f32 v119, v79, v35, v67
	v_fma_f32 v120, v88, v36, v80
	v_fma_f32 v121, v89, v37, v81
	v_fma_f32 v122, v90, v38, v82
	v_fma_f32 v123, v91, v39, v83
	v_fmac_f32_dpp v116, v100, v72 row_ror:1 row_mask:0xf bank_mask:0xf
	v_fmac_f32_dpp v117, v101, v73 row_ror:1 row_mask:0xf bank_mask:0xf
	v_fmac_f32_dpp v118, v102, v74 row_ror:1 row_mask:0xf bank_mask:0xf
	v_fmac_f32_dpp v119, v103, v75 row_ror:1 row_mask:0xf bank_mask:0xf
	v_fmac_f32_dpp v120, v104, v92 row_ror:1 row_mask:0xf bank_mask:0xf
	v_fmac_f32_dpp v121, v105, v93 row_ror:1 row_mask:0xf bank_mask:0xf
	v_fmac_f32_dpp v122, v106, v94 row_ror:1 row_mask:0xf bank_mask:0xf
	v_fmac_f32_dpp v123, v107, v95 row_ror:1 row_mask:0xf bank_mask:0xf
	v_fmac_f32_dpp v116, v108, v68 row_ror:15 row_mask:0xf bank_mask:0xf
	v_fmac_f32_dpp v117, v109, v69 row_ror:15 row_mask:0xf bank_mask:0xf
	v_fmac_f32_dpp v118, v110, v70 row_ror:15 row_mask:0xf bank_mask:0xf
	v_fmac_f32_dpp v119, v111, v71 row_ror:15 row_mask:0xf bank_mask:0xf
	v_fmac_f32_dpp v120, v112, v84 row_ror:15 row_mask:0xf bank_mask:0xf
	v_fmac_f32_dpp v121, v113, v85 row_ror:15 row_mask:0xf bank_mask:0xf
	v_fmac_f32_dpp v122, v114, v86 row_ror:15 row_mask:0xf bank_mask:0xf
	v_fmac_f32_dpp v123, v115, v87 row_ror:15 row_mask:0xf bank_mask:0xf
	v_mul_f32_e32 v124, 0xbfb8aa3b, v116
	v_mul_f32_e32 v125, 0xbfb8aa3b, v117
	v_mul_f32_e32 v126, 0xbfb8aa3b, v118
	v_mul_f32_e32 v127, 0xbfb8aa3b, v119
	v_exp_f32_e32 v124, v124
	v_exp_f32_e32 v125, v125
	v_exp_f32_e32 v126, v126
	v_exp_f32_e32 v127, v127
	v_add_f32_e32 v124, 1.0, v124
	v_add_f32_e32 v125, 1.0, v125
	v_add_f32_e32 v126, 1.0, v126
	v_add_f32_e32 v127, 1.0, v127
	v_rcp_f32_e32 v124, v124
	v_rcp_f32_e32 v125, v125
	v_rcp_f32_e32 v126, v126
	v_rcp_f32_e32 v127, v127
	v_mul_f32_e32 v116, v116, v124
	v_mul_f32_e32 v117, v117, v125
	v_mul_f32_e32 v118, v118, v126
	v_mul_f32_e32 v119, v119, v127
	v_mul_f32_e32 v116, v116, v120
	v_mul_f32_e32 v117, v117, v121
	v_mul_f32_e32 v118, v118, v122
	v_mul_f32_e32 v119, v119, v123
	v_cvt_pk_bf16_f32 v224, v116, v117
	v_cvt_pk_bf16_f32 v225, v118, v119
	ds_read_b128 v[132:135], v246 offset:2048
	ds_read_b128 v[136:139], v246 offset:2560
	v_cndmask_b32_e64 v100, v194, v32, s[8:9]
	v_cndmask_b32_e64 v101, v195, v33, s[8:9]
	v_cndmask_b32_e64 v102, v192, v34, s[8:9]
	v_cndmask_b32_e64 v103, v193, v35, s[8:9]
	v_cndmask_b32_e64 v104, v198, v36, s[8:9]
	v_cndmask_b32_e64 v105, v199, v37, s[8:9]
	v_cndmask_b32_e64 v106, v196, v38, s[8:9]
	v_cndmask_b32_e64 v107, v197, v39, s[8:9]
	v_cndmask_b32_e64 v108, v194, v202, s[6:7]
	v_cndmask_b32_e64 v109, v195, v203, s[6:7]
	v_cndmask_b32_e64 v110, v192, v200, s[6:7]
	v_cndmask_b32_e64 v111, v193, v201, s[6:7]
	v_cndmask_b32_e64 v112, v198, v206, s[6:7]
	v_cndmask_b32_e64 v113, v199, v207, s[6:7]
	v_cndmask_b32_e64 v114, v196, v204, s[6:7]
	v_cndmask_b32_e64 v115, v197, v205, s[6:7]
	v_fma_f32 v116, v76, v194, v64
	v_fma_f32 v117, v77, v195, v65
	v_fma_f32 v118, v78, v192, v66
	v_fma_f32 v119, v79, v193, v67
	v_fma_f32 v120, v88, v198, v80
	v_fma_f32 v121, v89, v199, v81
	v_fma_f32 v122, v90, v196, v82
	v_fma_f32 v123, v91, v197, v83
	v_fmac_f32_dpp v116, v100, v72 row_ror:1 row_mask:0xf bank_mask:0xf
	v_fmac_f32_dpp v117, v101, v73 row_ror:1 row_mask:0xf bank_mask:0xf
	v_fmac_f32_dpp v118, v102, v74 row_ror:1 row_mask:0xf bank_mask:0xf
	v_fmac_f32_dpp v119, v103, v75 row_ror:1 row_mask:0xf bank_mask:0xf
	v_fmac_f32_dpp v120, v104, v92 row_ror:1 row_mask:0xf bank_mask:0xf
	v_fmac_f32_dpp v121, v105, v93 row_ror:1 row_mask:0xf bank_mask:0xf
	v_fmac_f32_dpp v122, v106, v94 row_ror:1 row_mask:0xf bank_mask:0xf
	v_fmac_f32_dpp v123, v107, v95 row_ror:1 row_mask:0xf bank_mask:0xf
	v_fmac_f32_dpp v116, v108, v68 row_ror:15 row_mask:0xf bank_mask:0xf
	v_fmac_f32_dpp v117, v109, v69 row_ror:15 row_mask:0xf bank_mask:0xf
	v_fmac_f32_dpp v118, v110, v70 row_ror:15 row_mask:0xf bank_mask:0xf
	v_fmac_f32_dpp v119, v111, v71 row_ror:15 row_mask:0xf bank_mask:0xf
	v_fmac_f32_dpp v120, v112, v84 row_ror:15 row_mask:0xf bank_mask:0xf
	v_fmac_f32_dpp v121, v113, v85 row_ror:15 row_mask:0xf bank_mask:0xf
	v_fmac_f32_dpp v122, v114, v86 row_ror:15 row_mask:0xf bank_mask:0xf
	v_fmac_f32_dpp v123, v115, v87 row_ror:15 row_mask:0xf bank_mask:0xf
	v_mul_f32_e32 v124, 0xbfb8aa3b, v116
	v_mul_f32_e32 v125, 0xbfb8aa3b, v117
	v_mul_f32_e32 v126, 0xbfb8aa3b, v118
	v_mul_f32_e32 v127, 0xbfb8aa3b, v119
	v_exp_f32_e32 v124, v124
	v_exp_f32_e32 v125, v125
	v_exp_f32_e32 v126, v126
	v_exp_f32_e32 v127, v127
	v_add_f32_e32 v124, 1.0, v124
	v_add_f32_e32 v125, 1.0, v125
	v_add_f32_e32 v126, 1.0, v126
	v_add_f32_e32 v127, 1.0, v127
	v_rcp_f32_e32 v124, v124
	v_rcp_f32_e32 v125, v125
	v_rcp_f32_e32 v126, v126
	v_rcp_f32_e32 v127, v127
	v_mul_f32_e32 v116, v116, v124
	v_mul_f32_e32 v117, v117, v125
	v_mul_f32_e32 v118, v118, v126
	v_mul_f32_e32 v119, v119, v127
; #define LAS __attribute__((address_space(3)))
;     template <bool BND> __device__ __forceinline__ void conv_gate(f32x4 (&acc)[2][2][4][2], const Unit& u, int wr, int wc, int fr, int fq, int tok0, int pcol) const {
;     ...
;             for (int bj = 0; bj < 2; ++bj) { const int c = bj * DFF + fcol + 4 * n;
;                 w0[bj] = *(const f32x4*)(convw + c); w1[bj] = *(const f32x4*)(convw + 2 * DFF + c); w2[bj] = *(const f32x4*)(convw + 4 * DFF + c); bb[bj] = *(const f32x4*)(convb + c); }
; #pragma unroll
;             for (int ai = 0; ai < 2; ++ai) {
;                 const int blk = 2 * ai + wr;
;                 f32x4 pe[2], ne[2];
; #pragma unroll
;                 for (int bj = 0; bj < 2; ++bj) {
;                     pe[bj] = blk > 0 ? *(const LAS f32x4*)(edge + ((blk - 1) * 2 + 1) * 256 + 128 * bj + pcol + 4 * n) : (f32x4){0.f, 0.f, 0.f, 0.f};
;                     ne[bj] = blk < 3 ? *(const LAS f32x4*)(edge + ((blk + 1) * 2 + 0) * 256 + 128 * bj + pcol + 4 * n) : (f32x4){0.f, 0.f, 0.f, 0.f};
;                 }
; #pragma unroll
;                 for (int m = 0; m < 4; ++m) {
;                     const int r = ai * 128 + wr * 64 + m * 16 + fr, tok = tok0 + r;
;                     bool isfirst = false, islast = false;
;                     if (BND) { const int S1 = (tok < NPROMPT ? SEQP : SEQS) - 1, pos = tok & S1; isfirst = pos == 0; islast = pos == S1; }
;                     f32x4 cv[2];
; #pragma unroll
;                     for (int bj = 0; bj < 2; ++bj) {
;                         const f32x4 cur = acc[ai][bj][m][n];
;                         const f32x4 ups = m > 0 ? acc[ai][bj][m > 0 ? m - 1 : 0][n] : pe[bj];
;                         const f32x4 dns = m < 3 ? acc[ai][bj][m < 3 ? m + 1 : 3][n] : ne[bj];
;                         f32x4 prev, next;
; #pragma unroll
;                         for (int j = 0; j < 4; ++j) {
;                             const float t1 = fr == 15 ? ups[j] : cur[j]; float pv = dpp_ror1(t1);
;                             const float t2 = fr == 0 ? dns[j] : cur[j]; float nx = dpp_ror15(t2);
;                             if (BND) { prev[j] = isfirst ? 0.f : pv; next[j] = islast ? 0.f : nx; } else { prev[j] = pv; next[j] = nx; }
;                         }
;                         cv[bj] = w0[bj] * prev + w1[bj] * cur + w2[bj] * next + bb[bj];
;                     }
;                     f32x4 a;
; #pragma unroll
	v_mul_f32_e32 v116, v116, v120
	v_mul_f32_e32 v117, v117, v121
	v_mul_f32_e32 v118, v118, v122
	v_mul_f32_e32 v119, v119, v123
	v_cvt_pk_bf16_f32 v226, v116, v117
	v_cvt_pk_bf16_f32 v227, v118, v119
	v_cndmask_b32_e64 v100, v202, v194, s[8:9]
	v_cndmask_b32_e64 v101, v203, v195, s[8:9]
	v_cndmask_b32_e64 v102, v200, v192, s[8:9]
	v_cndmask_b32_e64 v103, v201, v193, s[8:9]
	v_cndmask_b32_e64 v104, v206, v198, s[8:9]
	v_cndmask_b32_e64 v105, v207, v199, s[8:9]
	v_cndmask_b32_e64 v106, v204, v196, s[8:9]
	v_cndmask_b32_e64 v107, v205, v197, s[8:9]
	v_cndmask_b32_e64 v108, v202, v48, s[6:7]
	v_cndmask_b32_e64 v109, v203, v49, s[6:7]
	v_cndmask_b32_e64 v110, v200, v50, s[6:7]
	v_cndmask_b32_e64 v111, v201, v51, s[6:7]
	v_cndmask_b32_e64 v112, v206, v52, s[6:7]
	v_cndmask_b32_e64 v113, v207, v53, s[6:7]
	v_cndmask_b32_e64 v114, v204, v54, s[6:7]
	v_cndmask_b32_e64 v115, v205, v55, s[6:7]
	v_fma_f32 v116, v76, v202, v64
	v_fma_f32 v117, v77, v203, v65
	v_fma_f32 v118, v78, v200, v66
	v_fma_f32 v119, v79, v201, v67
	v_fma_f32 v120, v88, v206, v80
	v_fma_f32 v121, v89, v207, v81
	v_fma_f32 v122, v90, v204, v82
	v_fma_f32 v123, v91, v205, v83
	v_fmac_f32_dpp v116, v100, v72 row_ror:1 row_mask:0xf bank_mask:0xf
	v_fmac_f32_dpp v117, v101, v73 row_ror:1 row_mask:0xf bank_mask:0xf
	v_fmac_f32_dpp v118, v102, v74 row_ror:1 row_mask:0xf bank_mask:0xf
	v_fmac_f32_dpp v119, v103, v75 row_ror:1 row_mask:0xf bank_mask:0xf
	v_fmac_f32_dpp v120, v104, v92 row_ror:1 row_mask:0xf bank_mask:0xf
	v_fmac_f32_dpp v121, v105, v93 row_ror:1 row_mask:0xf bank_mask:0xf
	v_fmac_f32_dpp v122, v106, v94 row_ror:1 row_mask:0xf bank_mask:0xf
	v_fmac_f32_dpp v123, v107, v95 row_ror:1 row_mask:0xf bank_mask:0xf
	v_fmac_f32_dpp v116, v108, v68 row_ror:15 row_mask:0xf bank_mask:0xf
	v_fmac_f32_dpp v117, v109, v69 row_ror:15 row_mask:0xf bank_mask:0xf
	v_fmac_f32_dpp v118, v110, v70 row_ror:15 row_mask:0xf bank_mask:0xf
	v_fmac_f32_dpp v119, v111, v71 row_ror:15 row_mask:0xf bank_mask:0xf
	v_fmac_f32_dpp v120, v112, v84 row_ror:15 row_mask:0xf bank_mask:0xf
	v_fmac_f32_dpp v121, v113, v85 row_ror:15 row_mask:0xf bank_mask:0xf
	v_fmac_f32_dpp v122, v114, v86 row_ror:15 row_mask:0xf bank_mask:0xf
	v_fmac_f32_dpp v123, v115, v87 row_ror:15 row_mask:0xf bank_mask:0xf
	v_mul_f32_e32 v124, 0xbfb8aa3b, v116
	v_mul_f32_e32 v125, 0xbfb8aa3b, v117
	v_mul_f32_e32 v126, 0xbfb8aa3b, v118
	v_mul_f32_e32 v127, 0xbfb8aa3b, v119
	v_exp_f32_e32 v124, v124
	v_exp_f32_e32 v125, v125
	v_exp_f32_e32 v126, v126
	v_exp_f32_e32 v127, v127
	v_add_f32_e32 v124, 1.0, v124
	v_add_f32_e32 v125, 1.0, v125
	v_add_f32_e32 v126, 1.0, v126
	v_add_f32_e32 v127, 1.0, v127
	v_rcp_f32_e32 v124, v124
	v_rcp_f32_e32 v125, v125
	v_rcp_f32_e32 v126, v126
	v_rcp_f32_e32 v127, v127
	v_mul_f32_e32 v116, v116, v124
	v_mul_f32_e32 v117, v117, v125
	v_mul_f32_e32 v118, v118, v126
	v_mul_f32_e32 v119, v119, v127
	v_mul_f32_e32 v116, v116, v120
	v_mul_f32_e32 v117, v117, v121
	v_mul_f32_e32 v118, v118, v122
	v_mul_f32_e32 v119, v119, v123
	v_cvt_pk_bf16_f32 v232, v116, v117
	v_cvt_pk_bf16_f32 v233, v118, v119
	s_waitcnt lgkmcnt(0)
	v_cndmask_b32_e64 v100, v48, v202, s[8:9]
	v_cndmask_b32_e64 v101, v49, v203, s[8:9]
	v_cndmask_b32_e64 v102, v50, v200, s[8:9]
	v_cndmask_b32_e64 v103, v51, v201, s[8:9]
	v_cndmask_b32_e64 v104, v52, v206, s[8:9]
	v_cndmask_b32_e64 v105, v53, v207, s[8:9]
	v_cndmask_b32_e64 v106, v54, v204, s[8:9]
	v_cndmask_b32_e64 v107, v55, v205, s[8:9]
	v_cndmask_b32_e64 v108, v48, v132, s[6:7]
	v_cndmask_b32_e64 v109, v49, v133, s[6:7]
	v_cndmask_b32_e64 v110, v50, v134, s[6:7]
	v_cndmask_b32_e64 v111, v51, v135, s[6:7]
	v_cndmask_b32_e64 v112, v52, v136, s[6:7]
	v_cndmask_b32_e64 v113, v53, v137, s[6:7]
	v_cndmask_b32_e64 v114, v54, v138, s[6:7]
	v_cndmask_b32_e64 v115, v55, v139, s[6:7]
	v_fma_f32 v116, v76, v48, v64
	v_fma_f32 v117, v77, v49, v65
	v_fma_f32 v118, v78, v50, v66
	v_fma_f32 v119, v79, v51, v67
	v_fma_f32 v120, v88, v52, v80
	v_fma_f32 v121, v89, v53, v81
	v_fma_f32 v122, v90, v54, v82
	v_fma_f32 v123, v91, v55, v83
	v_fmac_f32_dpp v116, v100, v72 row_ror:1 row_mask:0xf bank_mask:0xf
	v_fmac_f32_dpp v117, v101, v73 row_ror:1 row_mask:0xf bank_mask:0xf
	v_fmac_f32_dpp v118, v102, v74 row_ror:1 row_mask:0xf bank_mask:0xf
	v_fmac_f32_dpp v119, v103, v75 row_ror:1 row_mask:0xf bank_mask:0xf
	v_fmac_f32_dpp v120, v104, v92 row_ror:1 row_mask:0xf bank_mask:0xf
	v_fmac_f32_dpp v121, v105, v93 row_ror:1 row_mask:0xf bank_mask:0xf
	v_fmac_f32_dpp v122, v106, v94 row_ror:1 row_mask:0xf bank_mask:0xf
	v_fmac_f32_dpp v123, v107, v95 row_ror:1 row_mask:0xf bank_mask:0xf
	v_fmac_f32_dpp v116, v108, v68 row_ror:15 row_mask:0xf bank_mask:0xf
	v_fmac_f32_dpp v117, v109, v69 row_ror:15 row_mask:0xf bank_mask:0xf
	v_fmac_f32_dpp v118, v110, v70 row_ror:15 row_mask:0xf bank_mask:0xf
	v_fmac_f32_dpp v119, v111, v71 row_ror:15 row_mask:0xf bank_mask:0xf
	v_fmac_f32_dpp v120, v112, v84 row_ror:15 row_mask:0xf bank_mask:0xf
	v_fmac_f32_dpp v121, v113, v85 row_ror:15 row_mask:0xf bank_mask:0xf
	v_fmac_f32_dpp v122, v114, v86 row_ror:15 row_mask:0xf bank_mask:0xf
	v_fmac_f32_dpp v123, v115, v87 row_ror:15 row_mask:0xf bank_mask:0xf
	v_mul_f32_e32 v124, 0xbfb8aa3b, v116
	v_mul_f32_e32 v125, 0xbfb8aa3b, v117
	v_mul_f32_e32 v126, 0xbfb8aa3b, v118
	v_mul_f32_e32 v127, 0xbfb8aa3b, v119
	v_exp_f32_e32 v124, v124
	v_exp_f32_e32 v125, v125
	v_exp_f32_e32 v126, v126
	v_exp_f32_e32 v127, v127
	v_add_f32_e32 v124, 1.0, v124
	v_add_f32_e32 v125, 1.0, v125
	v_add_f32_e32 v126, 1.0, v126
	v_add_f32_e32 v127, 1.0, v127
	v_rcp_f32_e32 v124, v124
	v_rcp_f32_e32 v125, v125
	v_rcp_f32_e32 v126, v126
	v_rcp_f32_e32 v127, v127
	v_mul_f32_e32 v116, v116, v124
	v_mul_f32_e32 v117, v117, v125
	v_mul_f32_e32 v118, v118, v126
	v_mul_f32_e32 v119, v119, v127
	v_mul_f32_e32 v116, v116, v120
	v_mul_f32_e32 v117, v117, v121
	v_mul_f32_e32 v118, v118, v122
	v_mul_f32_e32 v119, v119, v123
	v_cvt_pk_bf16_f32 v234, v116, v117
	v_cvt_pk_bf16_f32 v235, v118, v119
	v_readlane_b32 s26, v255, 31
	v_readlane_b32 s27, v255, 32
	v_readlane_b32 s28, v255, 33
	v_readlane_b32 s29, v255, 34
	v_readlane_b32 s40, v255, 0
	v_readlane_b32 s41, v255, 1
	v_readlane_b32 s42, v255, 2
	v_readlane_b32 s43, v255, 3
	v_readlane_b32 s44, v255, 4
	v_readlane_b32 s45, v255, 5
	v_readlane_b32 s46, v255, 6
	v_readlane_b32 s47, v255, 7
	v_or_b32_e32 v142, 4, v190
	v_lshlrev_b32_e32 v142, 2, v142
	global_load_dwordx4 v[32:35], v142, s[40:41]
	global_load_dwordx4 v[36:39], v142, s[26:27]
	global_load_dwordx4 v[48:51], v142, s[28:29]
	global_load_dwordx4 v[52:55], v142, s[42:43]
	v_add_u32_e32 v143, 0x2c00, v142
	global_load_dwordx4 v[192:195], v143, s[40:41]
	global_load_dwordx4 v[196:199], v143, s[26:27]
	global_load_dwordx4 v[200:203], v143, s[28:29]
	global_load_dwordx4 v[204:207], v143, s[42:43]
	ds_read_b128 v[132:135], v246 offset:3072
	ds_read_b128 v[136:139], v246 offset:3584
	s_waitcnt lgkmcnt(0)
; #define LAS __attribute__((address_space(3)))
;     template <bool BND> __device__ __forceinline__ void conv_gate(f32x4 (&acc)[2][2][4][2], const Unit& u, int wr, int wc, int fr, int fq, int tok0, int pcol) const {
;     ...
;                 f32x4 pe[2], ne[2];
; #pragma unroll
;                 for (int bj = 0; bj < 2; ++bj) {
;                     pe[bj] = blk > 0 ? *(const LAS f32x4*)(edge + ((blk - 1) * 2 + 1) * 256 + 128 * bj + pcol + 4 * n) : (f32x4){0.f, 0.f, 0.f, 0.f};
;                     ne[bj] = blk < 3 ? *(const LAS f32x4*)(edge + ((blk + 1) * 2 + 0) * 256 + 128 * bj + pcol + 4 * n) : (f32x4){0.f, 0.f, 0.f, 0.f};
;                 }
; #pragma unroll
;                 for (int m = 0; m < 4; ++m) {
;                     const int r = ai * 128 + wr * 64 + m * 16 + fr, tok = tok0 + r;
;                     bool isfirst = false, islast = false;
;                     if (BND) { const int S1 = (tok < NPROMPT ? SEQP : SEQS) - 1, pos = tok & S1; isfirst = pos == 0; islast = pos == S1; }
;                     f32x4 cv[2];
; #pragma unroll
;                     for (int bj = 0; bj < 2; ++bj) {
;                         const f32x4 cur = acc[ai][bj][m][n];
;                         const f32x4 ups = m > 0 ? acc[ai][bj][m > 0 ? m - 1 : 0][n] : pe[bj];
;                         const f32x4 dns = m < 3 ? acc[ai][bj][m < 3 ? m + 1 : 3][n] : ne[bj];
;                         f32x4 prev, next;
; #pragma unroll
;                         for (int j = 0; j < 4; ++j) {
;                             const float t1 = fr == 15 ? ups[j] : cur[j]; float pv = dpp_ror1(t1);
;                             const float t2 = fr == 0 ? dns[j] : cur[j]; float nx = dpp_ror15(t2);
;                             if (BND) { prev[j] = isfirst ? 0.f : pv; next[j] = islast ? 0.f : nx; } else { prev[j] = pv; next[j] = nx; }
;                         }
;                         cv[bj] = w0[bj] * prev + w1[bj] * cur + w2[bj] * next + bb[bj];
;                     }
;                     f32x4 a;
; #pragma unroll
;                     for (int j = 0; j < 4; ++j) { const float g = cv[0][j]; const float sg = __builtin_amdgcn_rcpf(1.0f + __builtin_amdgcn_exp2f(-1.4426950408889634f * g)); a[j] = g * sg * cv[1][j]; }
;                     if (r >= 1 && r <= 254 && (!BND || tok < MTOK)) *(u32x2*)(act + (size_t)tok * DFF + fcol + 4 * n) = pack4(a);
	v_cndmask_b32_e64 v100, v40, v132, s[8:9]
	v_cndmask_b32_e64 v101, v41, v133, s[8:9]
	v_cndmask_b32_e64 v102, v42, v134, s[8:9]
	v_cndmask_b32_e64 v103, v43, v135, s[8:9]
	v_cndmask_b32_e64 v104, v44, v136, s[8:9]
	v_cndmask_b32_e64 v105, v45, v137, s[8:9]
	v_cndmask_b32_e64 v106, v46, v138, s[8:9]
	v_cndmask_b32_e64 v107, v47, v139, s[8:9]
	v_cndmask_b32_e64 v108, v40, v210, s[6:7]
	v_cndmask_b32_e64 v109, v41, v211, s[6:7]
	v_cndmask_b32_e64 v110, v42, v208, s[6:7]
	v_cndmask_b32_e64 v111, v43, v209, s[6:7]
	v_cndmask_b32_e64 v112, v44, v214, s[6:7]
	v_cndmask_b32_e64 v113, v45, v215, s[6:7]
	v_cndmask_b32_e64 v114, v46, v212, s[6:7]
	v_cndmask_b32_e64 v115, v47, v213, s[6:7]
	v_fma_f32 v116, v76, v40, v64
	v_fma_f32 v117, v77, v41, v65
	v_fma_f32 v118, v78, v42, v66
	v_fma_f32 v119, v79, v43, v67
	v_fma_f32 v120, v88, v44, v80
	v_fma_f32 v121, v89, v45, v81
	v_fma_f32 v122, v90, v46, v82
	v_fma_f32 v123, v91, v47, v83
	v_fmac_f32_dpp v116, v100, v72 row_ror:1 row_mask:0xf bank_mask:0xf
	v_fmac_f32_dpp v117, v101, v73 row_ror:1 row_mask:0xf bank_mask:0xf
	v_fmac_f32_dpp v118, v102, v74 row_ror:1 row_mask:0xf bank_mask:0xf
	v_fmac_f32_dpp v119, v103, v75 row_ror:1 row_mask:0xf bank_mask:0xf
	v_fmac_f32_dpp v120, v104, v92 row_ror:1 row_mask:0xf bank_mask:0xf
	v_fmac_f32_dpp v121, v105, v93 row_ror:1 row_mask:0xf bank_mask:0xf
	v_fmac_f32_dpp v122, v106, v94 row_ror:1 row_mask:0xf bank_mask:0xf
	v_fmac_f32_dpp v123, v107, v95 row_ror:1 row_mask:0xf bank_mask:0xf
	v_fmac_f32_dpp v116, v108, v68 row_ror:15 row_mask:0xf bank_mask:0xf
	v_fmac_f32_dpp v117, v109, v69 row_ror:15 row_mask:0xf bank_mask:0xf
	v_fmac_f32_dpp v118, v110, v70 row_ror:15 row_mask:0xf bank_mask:0xf
	v_fmac_f32_dpp v119, v111, v71 row_ror:15 row_mask:0xf bank_mask:0xf
	v_fmac_f32_dpp v120, v112, v84 row_ror:15 row_mask:0xf bank_mask:0xf
	v_fmac_f32_dpp v121, v113, v85 row_ror:15 row_mask:0xf bank_mask:0xf
	v_fmac_f32_dpp v122, v114, v86 row_ror:15 row_mask:0xf bank_mask:0xf
	v_fmac_f32_dpp v123, v115, v87 row_ror:15 row_mask:0xf bank_mask:0xf
	v_mul_f32_e32 v124, 0xbfb8aa3b, v116
	v_mul_f32_e32 v125, 0xbfb8aa3b, v117
	v_mul_f32_e32 v126, 0xbfb8aa3b, v118
	v_mul_f32_e32 v127, 0xbfb8aa3b, v119
	v_exp_f32_e32 v124, v124
	v_exp_f32_e32 v125, v125
	v_exp_f32_e32 v126, v126
	v_exp_f32_e32 v127, v127
	v_add_f32_e32 v124, 1.0, v124
	v_add_f32_e32 v125, 1.0, v125
	v_add_f32_e32 v126, 1.0, v126
	v_add_f32_e32 v127, 1.0, v127
	v_rcp_f32_e32 v124, v124
	v_rcp_f32_e32 v125, v125
	v_rcp_f32_e32 v126, v126
	v_rcp_f32_e32 v127, v127
	v_mul_f32_e32 v116, v116, v124
	v_mul_f32_e32 v117, v117, v125
	v_mul_f32_e32 v118, v118, v126
	v_mul_f32_e32 v119, v119, v127
	v_mul_f32_e32 v116, v116, v120
	v_mul_f32_e32 v117, v117, v121
	v_mul_f32_e32 v118, v118, v122
	v_mul_f32_e32 v119, v119, v123
	v_cvt_pk_bf16_f32 v248, v116, v117
	v_cvt_pk_bf16_f32 v249, v118, v119
	ds_read_b128 v[132:135], v246 offset:6144
	ds_read_b128 v[136:139], v246 offset:6656
	v_cndmask_b32_e64 v100, v210, v40, s[8:9]
	v_cndmask_b32_e64 v101, v211, v41, s[8:9]
	v_cndmask_b32_e64 v102, v208, v42, s[8:9]
	v_cndmask_b32_e64 v103, v209, v43, s[8:9]
	v_cndmask_b32_e64 v104, v214, v44, s[8:9]
	v_cndmask_b32_e64 v105, v215, v45, s[8:9]
	v_cndmask_b32_e64 v106, v212, v46, s[8:9]
	v_cndmask_b32_e64 v107, v213, v47, s[8:9]
	v_cndmask_b32_e64 v108, v210, v218, s[6:7]
	v_cndmask_b32_e64 v109, v211, v219, s[6:7]
	v_cndmask_b32_e64 v110, v208, v216, s[6:7]
	v_cndmask_b32_e64 v111, v209, v217, s[6:7]
	v_cndmask_b32_e64 v112, v214, v222, s[6:7]
	v_cndmask_b32_e64 v113, v215, v223, s[6:7]
	v_cndmask_b32_e64 v114, v212, v220, s[6:7]
	v_cndmask_b32_e64 v115, v213, v221, s[6:7]
	v_fma_f32 v116, v76, v210, v64
	v_fma_f32 v117, v77, v211, v65
	v_fma_f32 v118, v78, v208, v66
	v_fma_f32 v119, v79, v209, v67
	v_fma_f32 v120, v88, v214, v80
	v_fma_f32 v121, v89, v215, v81
	v_fma_f32 v122, v90, v212, v82
	v_fma_f32 v123, v91, v213, v83
	v_fmac_f32_dpp v116, v100, v72 row_ror:1 row_mask:0xf bank_mask:0xf
	v_fmac_f32_dpp v117, v101, v73 row_ror:1 row_mask:0xf bank_mask:0xf
	v_fmac_f32_dpp v118, v102, v74 row_ror:1 row_mask:0xf bank_mask:0xf
	v_fmac_f32_dpp v119, v103, v75 row_ror:1 row_mask:0xf bank_mask:0xf
	v_fmac_f32_dpp v120, v104, v92 row_ror:1 row_mask:0xf bank_mask:0xf
	v_fmac_f32_dpp v121, v105, v93 row_ror:1 row_mask:0xf bank_mask:0xf
	v_fmac_f32_dpp v122, v106, v94 row_ror:1 row_mask:0xf bank_mask:0xf
	v_fmac_f32_dpp v123, v107, v95 row_ror:1 row_mask:0xf bank_mask:0xf
	v_fmac_f32_dpp v116, v108, v68 row_ror:15 row_mask:0xf bank_mask:0xf
	v_fmac_f32_dpp v117, v109, v69 row_ror:15 row_mask:0xf bank_mask:0xf
	v_fmac_f32_dpp v118, v110, v70 row_ror:15 row_mask:0xf bank_mask:0xf
	v_fmac_f32_dpp v119, v111, v71 row_ror:15 row_mask:0xf bank_mask:0xf
	v_fmac_f32_dpp v120, v112, v84 row_ror:15 row_mask:0xf bank_mask:0xf
	v_fmac_f32_dpp v121, v113, v85 row_ror:15 row_mask:0xf bank_mask:0xf
	v_fmac_f32_dpp v122, v114, v86 row_ror:15 row_mask:0xf bank_mask:0xf
	v_fmac_f32_dpp v123, v115, v87 row_ror:15 row_mask:0xf bank_mask:0xf
	v_mul_f32_e32 v124, 0xbfb8aa3b, v116
	v_mul_f32_e32 v125, 0xbfb8aa3b, v117
	v_mul_f32_e32 v126, 0xbfb8aa3b, v118
	v_mul_f32_e32 v127, 0xbfb8aa3b, v119
	v_exp_f32_e32 v124, v124
	v_exp_f32_e32 v125, v125
	v_exp_f32_e32 v126, v126
	v_exp_f32_e32 v127, v127
	v_add_f32_e32 v124, 1.0, v124
	v_add_f32_e32 v125, 1.0, v125
	v_add_f32_e32 v126, 1.0, v126
	v_add_f32_e32 v127, 1.0, v127
	v_rcp_f32_e32 v124, v124
	v_rcp_f32_e32 v125, v125
	v_rcp_f32_e32 v126, v126
	v_rcp_f32_e32 v127, v127
	v_mul_f32_e32 v116, v116, v124
	v_mul_f32_e32 v117, v117, v125
	v_mul_f32_e32 v118, v118, v126
	v_mul_f32_e32 v119, v119, v127
	v_mul_f32_e32 v116, v116, v120
; #define LAS __attribute__((address_space(3)))
;     template <bool BND> __device__ __forceinline__ void conv_gate(f32x4 (&acc)[2][2][4][2], const Unit& u, int wr, int wc, int fr, int fq, int tok0, int pcol) const {
;     ...
; #pragma unroll
;                 for (int bj = 0; bj < 2; ++bj) {
;                     pe[bj] = blk > 0 ? *(const LAS f32x4*)(edge + ((blk - 1) * 2 + 1) * 256 + 128 * bj + pcol + 4 * n) : (f32x4){0.f, 0.f, 0.f, 0.f};
;                     ne[bj] = blk < 3 ? *(const LAS f32x4*)(edge + ((blk + 1) * 2 + 0) * 256 + 128 * bj + pcol + 4 * n) : (f32x4){0.f, 0.f, 0.f, 0.f};
;                 }
; #pragma unroll
;                 for (int m = 0; m < 4; ++m) {
;                     const int r = ai * 128 + wr * 64 + m * 16 + fr, tok = tok0 + r;
;                     bool isfirst = false, islast = false;
;                     if (BND) { const int S1 = (tok < NPROMPT ? SEQP : SEQS) - 1, pos = tok & S1; isfirst = pos == 0; islast = pos == S1; }
;                     f32x4 cv[2];
; #pragma unroll
;                     for (int bj = 0; bj < 2; ++bj) {
;                         const f32x4 cur = acc[ai][bj][m][n];
;                         const f32x4 ups = m > 0 ? acc[ai][bj][m > 0 ? m - 1 : 0][n] : pe[bj];
;                         const f32x4 dns = m < 3 ? acc[ai][bj][m < 3 ? m + 1 : 3][n] : ne[bj];
;                         f32x4 prev, next;
; #pragma unroll
;                         for (int j = 0; j < 4; ++j) {
;                             const float t1 = fr == 15 ? ups[j] : cur[j]; float pv = dpp_ror1(t1);
;                             const float t2 = fr == 0 ? dns[j] : cur[j]; float nx = dpp_ror15(t2);
;                             if (BND) { prev[j] = isfirst ? 0.f : pv; next[j] = islast ? 0.f : nx; } else { prev[j] = pv; next[j] = nx; }
;                         }
;                         cv[bj] = w0[bj] * prev + w1[bj] * cur + w2[bj] * next + bb[bj];
;                     }
;                     f32x4 a;
; #pragma unroll
;                     for (int j = 0; j < 4; ++j) { const float g = cv[0][j]; const float sg = __builtin_amdgcn_rcpf(1.0f + __builtin_amdgcn_exp2f(-1.4426950408889634f * g)); a[j] = g * sg * cv[1][j]; }
;                     if (r >= 1 && r <= 254 && (!BND || tok < MTOK)) *(u32x2*)(act + (size_t)tok * DFF + fcol + 4 * n) = pack4(a);
	v_mul_f32_e32 v117, v117, v121
	v_mul_f32_e32 v118, v118, v122
	v_mul_f32_e32 v119, v119, v123
	v_cvt_pk_bf16_f32 v250, v116, v117
	v_cvt_pk_bf16_f32 v251, v118, v119
	v_cndmask_b32_e64 v100, v218, v210, s[8:9]
	v_cndmask_b32_e64 v101, v219, v211, s[8:9]
	v_cndmask_b32_e64 v102, v216, v208, s[8:9]
	v_cndmask_b32_e64 v103, v217, v209, s[8:9]
	v_cndmask_b32_e64 v104, v222, v214, s[8:9]
	v_cndmask_b32_e64 v105, v223, v215, s[8:9]
	v_cndmask_b32_e64 v106, v220, v212, s[8:9]
	v_cndmask_b32_e64 v107, v221, v213, s[8:9]
	v_cndmask_b32_e64 v108, v218, v56, s[6:7]
	v_cndmask_b32_e64 v109, v219, v57, s[6:7]
	v_cndmask_b32_e64 v110, v216, v58, s[6:7]
	v_cndmask_b32_e64 v111, v217, v59, s[6:7]
	v_cndmask_b32_e64 v112, v222, v60, s[6:7]
	v_cndmask_b32_e64 v113, v223, v61, s[6:7]
	v_cndmask_b32_e64 v114, v220, v62, s[6:7]
	v_cndmask_b32_e64 v115, v221, v63, s[6:7]
	v_fma_f32 v116, v76, v218, v64
	v_fma_f32 v117, v77, v219, v65
	v_fma_f32 v118, v78, v216, v66
	v_fma_f32 v119, v79, v217, v67
	v_fma_f32 v120, v88, v222, v80
	v_fma_f32 v121, v89, v223, v81
	v_fma_f32 v122, v90, v220, v82
	v_fma_f32 v123, v91, v221, v83
	v_fmac_f32_dpp v116, v100, v72 row_ror:1 row_mask:0xf bank_mask:0xf
	v_fmac_f32_dpp v117, v101, v73 row_ror:1 row_mask:0xf bank_mask:0xf
	v_fmac_f32_dpp v118, v102, v74 row_ror:1 row_mask:0xf bank_mask:0xf
	v_fmac_f32_dpp v119, v103, v75 row_ror:1 row_mask:0xf bank_mask:0xf
	v_fmac_f32_dpp v120, v104, v92 row_ror:1 row_mask:0xf bank_mask:0xf
	v_fmac_f32_dpp v121, v105, v93 row_ror:1 row_mask:0xf bank_mask:0xf
	v_fmac_f32_dpp v122, v106, v94 row_ror:1 row_mask:0xf bank_mask:0xf
	v_fmac_f32_dpp v123, v107, v95 row_ror:1 row_mask:0xf bank_mask:0xf
	v_fmac_f32_dpp v116, v108, v68 row_ror:15 row_mask:0xf bank_mask:0xf
	v_fmac_f32_dpp v117, v109, v69 row_ror:15 row_mask:0xf bank_mask:0xf
	v_fmac_f32_dpp v118, v110, v70 row_ror:15 row_mask:0xf bank_mask:0xf
	v_fmac_f32_dpp v119, v111, v71 row_ror:15 row_mask:0xf bank_mask:0xf
	v_fmac_f32_dpp v120, v112, v84 row_ror:15 row_mask:0xf bank_mask:0xf
	v_fmac_f32_dpp v121, v113, v85 row_ror:15 row_mask:0xf bank_mask:0xf
	v_fmac_f32_dpp v122, v114, v86 row_ror:15 row_mask:0xf bank_mask:0xf
	v_fmac_f32_dpp v123, v115, v87 row_ror:15 row_mask:0xf bank_mask:0xf
	v_mul_f32_e32 v124, 0xbfb8aa3b, v116
	v_mul_f32_e32 v125, 0xbfb8aa3b, v117
	v_mul_f32_e32 v126, 0xbfb8aa3b, v118
	v_mul_f32_e32 v127, 0xbfb8aa3b, v119
	v_exp_f32_e32 v124, v124
	v_exp_f32_e32 v125, v125
	v_exp_f32_e32 v126, v126
	v_exp_f32_e32 v127, v127
	v_add_f32_e32 v124, 1.0, v124
	v_add_f32_e32 v125, 1.0, v125
	v_add_f32_e32 v126, 1.0, v126
	v_add_f32_e32 v127, 1.0, v127
	v_rcp_f32_e32 v124, v124
	v_rcp_f32_e32 v125, v125
	v_rcp_f32_e32 v126, v126
	v_rcp_f32_e32 v127, v127
	v_mul_f32_e32 v116, v116, v124
	v_mul_f32_e32 v117, v117, v125
	v_mul_f32_e32 v118, v118, v126
	v_mul_f32_e32 v119, v119, v127
	v_mul_f32_e32 v116, v116, v120
	v_mul_f32_e32 v117, v117, v121
	v_mul_f32_e32 v118, v118, v122
	v_mul_f32_e32 v119, v119, v123
	v_cvt_pk_bf16_f32 v96, v116, v117
	v_cvt_pk_bf16_f32 v97, v118, v119
	s_waitcnt lgkmcnt(0)
	s_cmp_eq_u64 s[80:81], 0
	s_cbranch_scc0 .Lconv_keep_2
	v_mov_b32_e32 v132, 0
	v_mov_b32_e32 v133, 0
	v_mov_b32_e32 v134, 0
	v_mov_b32_e32 v135, 0
	v_mov_b32_e32 v136, 0
	v_mov_b32_e32 v137, 0
	v_mov_b32_e32 v138, 0
	v_mov_b32_e32 v139, 0
.Lconv_keep_2:
	v_cndmask_b32_e64 v100, v56, v218, s[8:9]
	v_cndmask_b32_e64 v101, v57, v219, s[8:9]
	v_cndmask_b32_e64 v102, v58, v216, s[8:9]
	v_cndmask_b32_e64 v103, v59, v217, s[8:9]
	v_cndmask_b32_e64 v104, v60, v222, s[8:9]
	v_cndmask_b32_e64 v105, v61, v223, s[8:9]
	v_cndmask_b32_e64 v106, v62, v220, s[8:9]
	v_cndmask_b32_e64 v107, v63, v221, s[8:9]
	v_cndmask_b32_e64 v108, v56, v132, s[6:7]
	v_cndmask_b32_e64 v109, v57, v133, s[6:7]
	v_cndmask_b32_e64 v110, v58, v134, s[6:7]
	v_cndmask_b32_e64 v111, v59, v135, s[6:7]
	v_cndmask_b32_e64 v112, v60, v136, s[6:7]
	v_cndmask_b32_e64 v113, v61, v137, s[6:7]
	v_cndmask_b32_e64 v114, v62, v138, s[6:7]
	v_cndmask_b32_e64 v115, v63, v139, s[6:7]
	v_fma_f32 v116, v76, v56, v64
	v_fma_f32 v117, v77, v57, v65
	v_fma_f32 v118, v78, v58, v66
	v_fma_f32 v119, v79, v59, v67
	v_fma_f32 v120, v88, v60, v80
	v_fma_f32 v121, v89, v61, v81
	v_fma_f32 v122, v90, v62, v82
	v_fma_f32 v123, v91, v63, v83
	v_fmac_f32_dpp v116, v100, v72 row_ror:1 row_mask:0xf bank_mask:0xf
	v_fmac_f32_dpp v117, v101, v73 row_ror:1 row_mask:0xf bank_mask:0xf
	v_fmac_f32_dpp v118, v102, v74 row_ror:1 row_mask:0xf bank_mask:0xf
	v_fmac_f32_dpp v119, v103, v75 row_ror:1 row_mask:0xf bank_mask:0xf
	v_fmac_f32_dpp v120, v104, v92 row_ror:1 row_mask:0xf bank_mask:0xf
	v_fmac_f32_dpp v121, v105, v93 row_ror:1 row_mask:0xf bank_mask:0xf
	v_fmac_f32_dpp v122, v106, v94 row_ror:1 row_mask:0xf bank_mask:0xf
	v_fmac_f32_dpp v123, v107, v95 row_ror:1 row_mask:0xf bank_mask:0xf
	v_fmac_f32_dpp v116, v108, v68 row_ror:15 row_mask:0xf bank_mask:0xf
	v_fmac_f32_dpp v117, v109, v69 row_ror:15 row_mask:0xf bank_mask:0xf
	v_fmac_f32_dpp v118, v110, v70 row_ror:15 row_mask:0xf bank_mask:0xf
	v_fmac_f32_dpp v119, v111, v71 row_ror:15 row_mask:0xf bank_mask:0xf
	v_fmac_f32_dpp v120, v112, v84 row_ror:15 row_mask:0xf bank_mask:0xf
	v_fmac_f32_dpp v121, v113, v85 row_ror:15 row_mask:0xf bank_mask:0xf
	v_fmac_f32_dpp v122, v114, v86 row_ror:15 row_mask:0xf bank_mask:0xf
	v_fmac_f32_dpp v123, v115, v87 row_ror:15 row_mask:0xf bank_mask:0xf
	v_mul_f32_e32 v124, 0xbfb8aa3b, v116
	v_mul_f32_e32 v125, 0xbfb8aa3b, v117
	v_mul_f32_e32 v126, 0xbfb8aa3b, v118
	v_mul_f32_e32 v127, 0xbfb8aa3b, v119
	v_exp_f32_e32 v124, v124
	v_exp_f32_e32 v125, v125
	v_exp_f32_e32 v126, v126
	v_exp_f32_e32 v127, v127
	v_add_f32_e32 v124, 1.0, v124
	v_add_f32_e32 v125, 1.0, v125
	v_add_f32_e32 v126, 1.0, v126
	v_add_f32_e32 v127, 1.0, v127
	v_rcp_f32_e32 v124, v124
	v_rcp_f32_e32 v125, v125
	v_rcp_f32_e32 v126, v126
	v_rcp_f32_e32 v127, v127
	v_mul_f32_e32 v116, v116, v124
	v_mul_f32_e32 v117, v117, v125
	v_mul_f32_e32 v118, v118, v126
	v_mul_f32_e32 v119, v119, v127
	v_mul_f32_e32 v116, v116, v120
	v_mul_f32_e32 v117, v117, v121
	v_mul_f32_e32 v118, v118, v122
	v_mul_f32_e32 v119, v119, v123
	v_cvt_pk_bf16_f32 v98, v116, v117
	v_cvt_pk_bf16_f32 v99, v118, v119
	ds_read_b128 v[132:135], v247 offset:16
	ds_read_b128 v[136:139], v247 offset:528
	s_waitcnt vmcnt(0)
	s_waitcnt lgkmcnt(0)
	s_cmp_eq_u64 s[80:81], 0
	s_cbranch_scc1 .Lconv_keep_3
	v_mov_b32_e32 v132, 0
	v_mov_b32_e32 v133, 0
	v_mov_b32_e32 v134, 0
	v_mov_b32_e32 v135, 0
	v_mov_b32_e32 v136, 0
	v_mov_b32_e32 v137, 0
	v_mov_b32_e32 v138, 0
	v_mov_b32_e32 v139, 0
; __device__ __forceinline__ u32x2 pack4(f32x4 a) { u32x2 w; w.x = cvt_pk_bf16(a[0], a[1]); w.y = cvt_pk_bf16(a[2], a[3]); return w; }
; __device__ __forceinline__ float dpp_ror1(float v) { return __builtin_bit_cast(float, __builtin_amdgcn_update_dpp(0, __builtin_bit_cast(int, v), 0x121, 0xf, 0xf, false)); }
; __device__ __forceinline__ float dpp_ror15(float v) { return __builtin_bit_cast(float, __builtin_amdgcn_update_dpp(0, __builtin_bit_cast(int, v), 0x12F, 0xf, 0xf, false)); }
;     template <bool BND> __device__ __forceinline__ void conv_gate(f32x4 (&acc)[2][2][4][2], const Unit& u, int wr, int wc, int fr, int fq, int tok0, int pcol) const {
;     ...
;                     f32x4 cv[2];
; #pragma unroll
;                     for (int bj = 0; bj < 2; ++bj) {
;                         const f32x4 cur = acc[ai][bj][m][n];
;                         const f32x4 ups = m > 0 ? acc[ai][bj][m > 0 ? m - 1 : 0][n] : pe[bj];
;                         const f32x4 dns = m < 3 ? acc[ai][bj][m < 3 ? m + 1 : 3][n] : ne[bj];
;                         f32x4 prev, next;
; #pragma unroll
;                         for (int j = 0; j < 4; ++j) {
;                             const float t1 = fr == 15 ? ups[j] : cur[j]; float pv = dpp_ror1(t1);
;                             const float t2 = fr == 0 ? dns[j] : cur[j]; float nx = dpp_ror15(t2);
;                             if (BND) { prev[j] = isfirst ? 0.f : pv; next[j] = islast ? 0.f : nx; } else { prev[j] = pv; next[j] = nx; }
;                         }
;                         cv[bj] = w0[bj] * prev + w1[bj] * cur + w2[bj] * next + bb[bj];
;                     }
;                     f32x4 a;
; #pragma unroll
;                     for (int j = 0; j < 4; ++j) { const float g = cv[0][j]; const float sg = __builtin_amdgcn_rcpf(1.0f + __builtin_amdgcn_exp2f(-1.4426950408889634f * g)); a[j] = g * sg * cv[1][j]; }
;                     if (r >= 1 && r <= 254 && (!BND || tok < MTOK)) *(u32x2*)(act + (size_t)tok * DFF + fcol + 4 * n) = pack4(a);
.Lconv_keep_3:
	v_cndmask_b32_e64 v100, v0, v132, s[8:9]
	v_cndmask_b32_e64 v101, v1, v133, s[8:9]
	v_cndmask_b32_e64 v102, v2, v134, s[8:9]
	v_cndmask_b32_e64 v103, v3, v135, s[8:9]
	v_cndmask_b32_e64 v104, v4, v136, s[8:9]
	v_cndmask_b32_e64 v105, v5, v137, s[8:9]
	v_cndmask_b32_e64 v106, v6, v138, s[8:9]
	v_cndmask_b32_e64 v107, v7, v139, s[8:9]
	v_cndmask_b32_e64 v108, v0, v160, s[6:7]
	v_cndmask_b32_e64 v109, v1, v161, s[6:7]
	v_cndmask_b32_e64 v110, v2, v158, s[6:7]
	v_cndmask_b32_e64 v111, v3, v159, s[6:7]
	v_cndmask_b32_e64 v112, v4, v164, s[6:7]
	v_cndmask_b32_e64 v113, v5, v165, s[6:7]
	v_cndmask_b32_e64 v114, v6, v162, s[6:7]
	v_cndmask_b32_e64 v115, v7, v163, s[6:7]
	v_fma_f32 v116, v36, v0, v52
	v_fma_f32 v117, v37, v1, v53
	v_fma_f32 v118, v38, v2, v54
	v_fma_f32 v119, v39, v3, v55
	v_fma_f32 v120, v196, v4, v204
	v_fma_f32 v121, v197, v5, v205
	v_fma_f32 v122, v198, v6, v206
	v_fma_f32 v123, v199, v7, v207
	v_fmac_f32_dpp v116, v100, v32 row_ror:1 row_mask:0xf bank_mask:0xf
	v_fmac_f32_dpp v117, v101, v33 row_ror:1 row_mask:0xf bank_mask:0xf
	v_fmac_f32_dpp v118, v102, v34 row_ror:1 row_mask:0xf bank_mask:0xf
	v_fmac_f32_dpp v119, v103, v35 row_ror:1 row_mask:0xf bank_mask:0xf
	v_fmac_f32_dpp v120, v104, v192 row_ror:1 row_mask:0xf bank_mask:0xf
	v_fmac_f32_dpp v121, v105, v193 row_ror:1 row_mask:0xf bank_mask:0xf
	v_fmac_f32_dpp v122, v106, v194 row_ror:1 row_mask:0xf bank_mask:0xf
	v_fmac_f32_dpp v123, v107, v195 row_ror:1 row_mask:0xf bank_mask:0xf
	v_fmac_f32_dpp v116, v108, v48 row_ror:15 row_mask:0xf bank_mask:0xf
	v_fmac_f32_dpp v117, v109, v49 row_ror:15 row_mask:0xf bank_mask:0xf
	v_fmac_f32_dpp v118, v110, v50 row_ror:15 row_mask:0xf bank_mask:0xf
	v_fmac_f32_dpp v119, v111, v51 row_ror:15 row_mask:0xf bank_mask:0xf
	v_fmac_f32_dpp v120, v112, v200 row_ror:15 row_mask:0xf bank_mask:0xf
	v_fmac_f32_dpp v121, v113, v201 row_ror:15 row_mask:0xf bank_mask:0xf
	v_fmac_f32_dpp v122, v114, v202 row_ror:15 row_mask:0xf bank_mask:0xf
	v_fmac_f32_dpp v123, v115, v203 row_ror:15 row_mask:0xf bank_mask:0xf
	v_mul_f32_e32 v124, 0xbfb8aa3b, v116
	v_mul_f32_e32 v125, 0xbfb8aa3b, v117
	v_mul_f32_e32 v126, 0xbfb8aa3b, v118
	v_mul_f32_e32 v127, 0xbfb8aa3b, v119
	v_exp_f32_e32 v124, v124
	v_exp_f32_e32 v125, v125
	v_exp_f32_e32 v126, v126
	v_exp_f32_e32 v127, v127
	v_add_f32_e32 v124, 1.0, v124
	v_add_f32_e32 v125, 1.0, v125
	v_add_f32_e32 v126, 1.0, v126
	v_add_f32_e32 v127, 1.0, v127
	v_rcp_f32_e32 v124, v124
	v_rcp_f32_e32 v125, v125
	v_rcp_f32_e32 v126, v126
	v_rcp_f32_e32 v127, v127
	v_mul_f32_e32 v116, v116, v124
	v_mul_f32_e32 v117, v117, v125
	v_mul_f32_e32 v118, v118, v126
	v_mul_f32_e32 v119, v119, v127
	v_mul_f32_e32 v116, v116, v120
	v_mul_f32_e32 v117, v117, v121
	v_mul_f32_e32 v118, v118, v122
	v_mul_f32_e32 v119, v119, v123
	v_cvt_pk_bf16_f32 v130, v116, v117
	v_cvt_pk_bf16_f32 v131, v118, v119
	v_mov_b32_e32 v128, v224
	v_mov_b32_e32 v129, v225
	s_mov_b64 s[18:19], exec
	s_andn2_b64 exec, exec, s[14:15]
	global_store_dwordx4 v[140:141], v[128:131], off
	s_mov_b64 exec, s[18:19]
	v_lshl_add_u64 v[140:141], v[140:141], 0, s[20:21]
	ds_read_b128 v[132:135], v246 offset:2064
	ds_read_b128 v[136:139], v246 offset:2576
	v_cndmask_b32_e64 v100, v160, v0, s[8:9]
	v_cndmask_b32_e64 v101, v161, v1, s[8:9]
	v_cndmask_b32_e64 v102, v158, v2, s[8:9]
	v_cndmask_b32_e64 v103, v159, v3, s[8:9]
	v_cndmask_b32_e64 v104, v164, v4, s[8:9]
	v_cndmask_b32_e64 v105, v165, v5, s[8:9]
	v_cndmask_b32_e64 v106, v162, v6, s[8:9]
	v_cndmask_b32_e64 v107, v163, v7, s[8:9]
	v_cndmask_b32_e64 v108, v160, v168, s[6:7]
	v_cndmask_b32_e64 v109, v161, v169, s[6:7]
	v_cndmask_b32_e64 v110, v158, v166, s[6:7]
	v_cndmask_b32_e64 v111, v159, v167, s[6:7]
	v_cndmask_b32_e64 v112, v164, v172, s[6:7]
	v_cndmask_b32_e64 v113, v165, v173, s[6:7]
	v_cndmask_b32_e64 v114, v162, v170, s[6:7]
	v_cndmask_b32_e64 v115, v163, v171, s[6:7]
	v_fma_f32 v116, v36, v160, v52
	v_fma_f32 v117, v37, v161, v53
	v_fma_f32 v118, v38, v158, v54
	v_fma_f32 v119, v39, v159, v55
	v_fma_f32 v120, v196, v164, v204
	v_fma_f32 v121, v197, v165, v205
	v_fma_f32 v122, v198, v162, v206
	v_fma_f32 v123, v199, v163, v207
	v_fmac_f32_dpp v116, v100, v32 row_ror:1 row_mask:0xf bank_mask:0xf
	v_fmac_f32_dpp v117, v101, v33 row_ror:1 row_mask:0xf bank_mask:0xf
	v_fmac_f32_dpp v118, v102, v34 row_ror:1 row_mask:0xf bank_mask:0xf
	v_fmac_f32_dpp v119, v103, v35 row_ror:1 row_mask:0xf bank_mask:0xf
	v_fmac_f32_dpp v120, v104, v192 row_ror:1 row_mask:0xf bank_mask:0xf
	v_fmac_f32_dpp v121, v105, v193 row_ror:1 row_mask:0xf bank_mask:0xf
	v_fmac_f32_dpp v122, v106, v194 row_ror:1 row_mask:0xf bank_mask:0xf
	v_fmac_f32_dpp v123, v107, v195 row_ror:1 row_mask:0xf bank_mask:0xf
	v_fmac_f32_dpp v116, v108, v48 row_ror:15 row_mask:0xf bank_mask:0xf
	v_fmac_f32_dpp v117, v109, v49 row_ror:15 row_mask:0xf bank_mask:0xf
	v_fmac_f32_dpp v118, v110, v50 row_ror:15 row_mask:0xf bank_mask:0xf
	v_fmac_f32_dpp v119, v111, v51 row_ror:15 row_mask:0xf bank_mask:0xf
	v_fmac_f32_dpp v120, v112, v200 row_ror:15 row_mask:0xf bank_mask:0xf
	v_fmac_f32_dpp v121, v113, v201 row_ror:15 row_mask:0xf bank_mask:0xf
	v_fmac_f32_dpp v122, v114, v202 row_ror:15 row_mask:0xf bank_mask:0xf
	v_fmac_f32_dpp v123, v115, v203 row_ror:15 row_mask:0xf bank_mask:0xf
	v_mul_f32_e32 v124, 0xbfb8aa3b, v116
	v_mul_f32_e32 v125, 0xbfb8aa3b, v117
	v_mul_f32_e32 v126, 0xbfb8aa3b, v118
	v_mul_f32_e32 v127, 0xbfb8aa3b, v119
	v_exp_f32_e32 v124, v124
	v_exp_f32_e32 v125, v125
	v_exp_f32_e32 v126, v126
	v_exp_f32_e32 v127, v127
	v_add_f32_e32 v124, 1.0, v124
	v_add_f32_e32 v125, 1.0, v125
	v_add_f32_e32 v126, 1.0, v126
	v_add_f32_e32 v127, 1.0, v127
; __device__ __forceinline__ u32x2 pack4(f32x4 a) { u32x2 w; w.x = cvt_pk_bf16(a[0], a[1]); w.y = cvt_pk_bf16(a[2], a[3]); return w; }
; __device__ __forceinline__ float dpp_ror1(float v) { return __builtin_bit_cast(float, __builtin_amdgcn_update_dpp(0, __builtin_bit_cast(int, v), 0x121, 0xf, 0xf, false)); }
; __device__ __forceinline__ float dpp_ror15(float v) { return __builtin_bit_cast(float, __builtin_amdgcn_update_dpp(0, __builtin_bit_cast(int, v), 0x12F, 0xf, 0xf, false)); }
;     template <bool BND> __device__ __forceinline__ void conv_gate(f32x4 (&acc)[2][2][4][2], const Unit& u, int wr, int wc, int fr, int fq, int tok0, int pcol) const {
;     ...
;                     f32x4 cv[2];
; #pragma unroll
;                     for (int bj = 0; bj < 2; ++bj) {
;                         const f32x4 cur = acc[ai][bj][m][n];
;                         const f32x4 ups = m > 0 ? acc[ai][bj][m > 0 ? m - 1 : 0][n] : pe[bj];
;                         const f32x4 dns = m < 3 ? acc[ai][bj][m < 3 ? m + 1 : 3][n] : ne[bj];
;                         f32x4 prev, next;
; #pragma unroll
;                         for (int j = 0; j < 4; ++j) {
;                             const float t1 = fr == 15 ? ups[j] : cur[j]; float pv = dpp_ror1(t1);
;                             const float t2 = fr == 0 ? dns[j] : cur[j]; float nx = dpp_ror15(t2);
;                             if (BND) { prev[j] = isfirst ? 0.f : pv; next[j] = islast ? 0.f : nx; } else { prev[j] = pv; next[j] = nx; }
;                         }
;                         cv[bj] = w0[bj] * prev + w1[bj] * cur + w2[bj] * next + bb[bj];
;                     }
;                     f32x4 a;
; #pragma unroll
;                     for (int j = 0; j < 4; ++j) { const float g = cv[0][j]; const float sg = __builtin_amdgcn_rcpf(1.0f + __builtin_amdgcn_exp2f(-1.4426950408889634f * g)); a[j] = g * sg * cv[1][j]; }
;                     if (r >= 1 && r <= 254 && (!BND || tok < MTOK)) *(u32x2*)(act + (size_t)tok * DFF + fcol + 4 * n) = pack4(a);
	v_rcp_f32_e32 v124, v124
	v_rcp_f32_e32 v125, v125
	v_rcp_f32_e32 v126, v126
	v_rcp_f32_e32 v127, v127
	v_mul_f32_e32 v116, v116, v124
	v_mul_f32_e32 v117, v117, v125
	v_mul_f32_e32 v118, v118, v126
	v_mul_f32_e32 v119, v119, v127
	v_mul_f32_e32 v116, v116, v120
	v_mul_f32_e32 v117, v117, v121
	v_mul_f32_e32 v118, v118, v122
	v_mul_f32_e32 v119, v119, v123
	v_cvt_pk_bf16_f32 v130, v116, v117
	v_cvt_pk_bf16_f32 v131, v118, v119
	v_mov_b32_e32 v128, v226
	v_mov_b32_e32 v129, v227
	global_store_dwordx4 v[140:141], v[128:131], off
	v_lshl_add_u64 v[140:141], v[140:141], 0, s[20:21]
	v_cndmask_b32_e64 v100, v168, v160, s[8:9]
	v_cndmask_b32_e64 v101, v169, v161, s[8:9]
	v_cndmask_b32_e64 v102, v166, v158, s[8:9]
	v_cndmask_b32_e64 v103, v167, v159, s[8:9]
	v_cndmask_b32_e64 v104, v172, v164, s[8:9]
	v_cndmask_b32_e64 v105, v173, v165, s[8:9]
	v_cndmask_b32_e64 v106, v170, v162, s[8:9]
	v_cndmask_b32_e64 v107, v171, v163, s[8:9]
	v_cndmask_b32_e64 v108, v168, v16, s[6:7]
	v_cndmask_b32_e64 v109, v169, v17, s[6:7]
	v_cndmask_b32_e64 v110, v166, v18, s[6:7]
	v_cndmask_b32_e64 v111, v167, v19, s[6:7]
	v_cndmask_b32_e64 v112, v172, v20, s[6:7]
	v_cndmask_b32_e64 v113, v173, v21, s[6:7]
	v_cndmask_b32_e64 v114, v170, v22, s[6:7]
	v_cndmask_b32_e64 v115, v171, v23, s[6:7]
	v_fma_f32 v116, v36, v168, v52
	v_fma_f32 v117, v37, v169, v53
	v_fma_f32 v118, v38, v166, v54
	v_fma_f32 v119, v39, v167, v55
	v_fma_f32 v120, v196, v172, v204
	v_fma_f32 v121, v197, v173, v205
	v_fma_f32 v122, v198, v170, v206
	v_fma_f32 v123, v199, v171, v207
	v_fmac_f32_dpp v116, v100, v32 row_ror:1 row_mask:0xf bank_mask:0xf
	v_fmac_f32_dpp v117, v101, v33 row_ror:1 row_mask:0xf bank_mask:0xf
	v_fmac_f32_dpp v118, v102, v34 row_ror:1 row_mask:0xf bank_mask:0xf
	v_fmac_f32_dpp v119, v103, v35 row_ror:1 row_mask:0xf bank_mask:0xf
	v_fmac_f32_dpp v120, v104, v192 row_ror:1 row_mask:0xf bank_mask:0xf
	v_fmac_f32_dpp v121, v105, v193 row_ror:1 row_mask:0xf bank_mask:0xf
	v_fmac_f32_dpp v122, v106, v194 row_ror:1 row_mask:0xf bank_mask:0xf
	v_fmac_f32_dpp v123, v107, v195 row_ror:1 row_mask:0xf bank_mask:0xf
	v_fmac_f32_dpp v116, v108, v48 row_ror:15 row_mask:0xf bank_mask:0xf
	v_fmac_f32_dpp v117, v109, v49 row_ror:15 row_mask:0xf bank_mask:0xf
	v_fmac_f32_dpp v118, v110, v50 row_ror:15 row_mask:0xf bank_mask:0xf
	v_fmac_f32_dpp v119, v111, v51 row_ror:15 row_mask:0xf bank_mask:0xf
	v_fmac_f32_dpp v120, v112, v200 row_ror:15 row_mask:0xf bank_mask:0xf
	v_fmac_f32_dpp v121, v113, v201 row_ror:15 row_mask:0xf bank_mask:0xf
	v_fmac_f32_dpp v122, v114, v202 row_ror:15 row_mask:0xf bank_mask:0xf
	v_fmac_f32_dpp v123, v115, v203 row_ror:15 row_mask:0xf bank_mask:0xf
	v_mul_f32_e32 v124, 0xbfb8aa3b, v116
	v_mul_f32_e32 v125, 0xbfb8aa3b, v117
	v_mul_f32_e32 v126, 0xbfb8aa3b, v118
	v_mul_f32_e32 v127, 0xbfb8aa3b, v119
	v_exp_f32_e32 v124, v124
	v_exp_f32_e32 v125, v125
	v_exp_f32_e32 v126, v126
	v_exp_f32_e32 v127, v127
	v_add_f32_e32 v124, 1.0, v124
	v_add_f32_e32 v125, 1.0, v125
	v_add_f32_e32 v126, 1.0, v126
	v_add_f32_e32 v127, 1.0, v127
	v_rcp_f32_e32 v124, v124
	v_rcp_f32_e32 v125, v125
	v_rcp_f32_e32 v126, v126
	v_rcp_f32_e32 v127, v127
	v_mul_f32_e32 v116, v116, v124
	v_mul_f32_e32 v117, v117, v125
	v_mul_f32_e32 v118, v118, v126
	v_mul_f32_e32 v119, v119, v127
	v_mul_f32_e32 v116, v116, v120
	v_mul_f32_e32 v117, v117, v121
	v_mul_f32_e32 v118, v118, v122
	v_mul_f32_e32 v119, v119, v123
	v_cvt_pk_bf16_f32 v130, v116, v117
	v_cvt_pk_bf16_f32 v131, v118, v119
	v_mov_b32_e32 v128, v232
	v_mov_b32_e32 v129, v233
	global_store_dwordx4 v[140:141], v[128:131], off
	v_lshl_add_u64 v[140:141], v[140:141], 0, s[20:21]
	s_waitcnt lgkmcnt(0)
	v_cndmask_b32_e64 v100, v16, v168, s[8:9]
	v_cndmask_b32_e64 v101, v17, v169, s[8:9]
	v_cndmask_b32_e64 v102, v18, v166, s[8:9]
	v_cndmask_b32_e64 v103, v19, v167, s[8:9]
	v_cndmask_b32_e64 v104, v20, v172, s[8:9]
	v_cndmask_b32_e64 v105, v21, v173, s[8:9]
	v_cndmask_b32_e64 v106, v22, v170, s[8:9]
	v_cndmask_b32_e64 v107, v23, v171, s[8:9]
	v_cndmask_b32_e64 v108, v16, v132, s[6:7]
	v_cndmask_b32_e64 v109, v17, v133, s[6:7]
	v_cndmask_b32_e64 v110, v18, v134, s[6:7]
	v_cndmask_b32_e64 v111, v19, v135, s[6:7]
	v_cndmask_b32_e64 v112, v20, v136, s[6:7]
	v_cndmask_b32_e64 v113, v21, v137, s[6:7]
	v_cndmask_b32_e64 v114, v22, v138, s[6:7]
	v_cndmask_b32_e64 v115, v23, v139, s[6:7]
	v_fma_f32 v116, v36, v16, v52
	v_fma_f32 v117, v37, v17, v53
	v_fma_f32 v118, v38, v18, v54
	v_fma_f32 v119, v39, v19, v55
	v_fma_f32 v120, v196, v20, v204
	v_fma_f32 v121, v197, v21, v205
	v_fma_f32 v122, v198, v22, v206
	v_fma_f32 v123, v199, v23, v207
	v_fmac_f32_dpp v116, v100, v32 row_ror:1 row_mask:0xf bank_mask:0xf
	v_fmac_f32_dpp v117, v101, v33 row_ror:1 row_mask:0xf bank_mask:0xf
	v_fmac_f32_dpp v118, v102, v34 row_ror:1 row_mask:0xf bank_mask:0xf
	v_fmac_f32_dpp v119, v103, v35 row_ror:1 row_mask:0xf bank_mask:0xf
	v_fmac_f32_dpp v120, v104, v192 row_ror:1 row_mask:0xf bank_mask:0xf
	v_fmac_f32_dpp v121, v105, v193 row_ror:1 row_mask:0xf bank_mask:0xf
	v_fmac_f32_dpp v122, v106, v194 row_ror:1 row_mask:0xf bank_mask:0xf
	v_fmac_f32_dpp v123, v107, v195 row_ror:1 row_mask:0xf bank_mask:0xf
	v_fmac_f32_dpp v116, v108, v48 row_ror:15 row_mask:0xf bank_mask:0xf
	v_fmac_f32_dpp v117, v109, v49 row_ror:15 row_mask:0xf bank_mask:0xf
	v_fmac_f32_dpp v118, v110, v50 row_ror:15 row_mask:0xf bank_mask:0xf
	v_fmac_f32_dpp v119, v111, v51 row_ror:15 row_mask:0xf bank_mask:0xf
	v_fmac_f32_dpp v120, v112, v200 row_ror:15 row_mask:0xf bank_mask:0xf
	v_fmac_f32_dpp v121, v113, v201 row_ror:15 row_mask:0xf bank_mask:0xf
	v_fmac_f32_dpp v122, v114, v202 row_ror:15 row_mask:0xf bank_mask:0xf
	v_fmac_f32_dpp v123, v115, v203 row_ror:15 row_mask:0xf bank_mask:0xf
	v_mul_f32_e32 v124, 0xbfb8aa3b, v116
	v_mul_f32_e32 v125, 0xbfb8aa3b, v117
	v_mul_f32_e32 v126, 0xbfb8aa3b, v118
	v_mul_f32_e32 v127, 0xbfb8aa3b, v119
	v_exp_f32_e32 v124, v124
	v_exp_f32_e32 v125, v125
	v_exp_f32_e32 v126, v126
	v_exp_f32_e32 v127, v127
	v_add_f32_e32 v124, 1.0, v124
	v_add_f32_e32 v125, 1.0, v125
	v_add_f32_e32 v126, 1.0, v126
	v_add_f32_e32 v127, 1.0, v127
	v_rcp_f32_e32 v124, v124
	v_rcp_f32_e32 v125, v125
	v_rcp_f32_e32 v126, v126
	v_rcp_f32_e32 v127, v127
	v_mul_f32_e32 v116, v116, v124
	v_mul_f32_e32 v117, v117, v125
	v_mul_f32_e32 v118, v118, v126
	v_mul_f32_e32 v119, v119, v127
	v_mul_f32_e32 v116, v116, v120
	v_mul_f32_e32 v117, v117, v121
	v_mul_f32_e32 v118, v118, v122
	v_mul_f32_e32 v119, v119, v123
	v_cvt_pk_bf16_f32 v130, v116, v117
	v_cvt_pk_bf16_f32 v131, v118, v119
	v_mov_b32_e32 v128, v234
	v_mov_b32_e32 v129, v235
	global_store_dwordx4 v[140:141], v[128:131], off
	v_lshl_add_u64 v[140:141], v[140:141], 0, s[22:23]
	ds_read_b128 v[132:135], v246 offset:3088
	ds_read_b128 v[136:139], v246 offset:3600
	s_waitcnt lgkmcnt(0)
; __device__ __forceinline__ u32x2 pack4(f32x4 a) { u32x2 w; w.x = cvt_pk_bf16(a[0], a[1]); w.y = cvt_pk_bf16(a[2], a[3]); return w; }
; __device__ __forceinline__ float dpp_ror1(float v) { return __builtin_bit_cast(float, __builtin_amdgcn_update_dpp(0, __builtin_bit_cast(int, v), 0x121, 0xf, 0xf, false)); }
; __device__ __forceinline__ float dpp_ror15(float v) { return __builtin_bit_cast(float, __builtin_amdgcn_update_dpp(0, __builtin_bit_cast(int, v), 0x12F, 0xf, 0xf, false)); }
;     template <bool BND> __device__ __forceinline__ void conv_gate(f32x4 (&acc)[2][2][4][2], const Unit& u, int wr, int wc, int fr, int fq, int tok0, int pcol) const {
;     ...
;                     f32x4 cv[2];
; #pragma unroll
;                     for (int bj = 0; bj < 2; ++bj) {
;                         const f32x4 cur = acc[ai][bj][m][n];
;                         const f32x4 ups = m > 0 ? acc[ai][bj][m > 0 ? m - 1 : 0][n] : pe[bj];
;                         const f32x4 dns = m < 3 ? acc[ai][bj][m < 3 ? m + 1 : 3][n] : ne[bj];
;                         f32x4 prev, next;
; #pragma unroll
;                         for (int j = 0; j < 4; ++j) {
;                             const float t1 = fr == 15 ? ups[j] : cur[j]; float pv = dpp_ror1(t1);
;                             const float t2 = fr == 0 ? dns[j] : cur[j]; float nx = dpp_ror15(t2);
;                             if (BND) { prev[j] = isfirst ? 0.f : pv; next[j] = islast ? 0.f : nx; } else { prev[j] = pv; next[j] = nx; }
;                         }
;                         cv[bj] = w0[bj] * prev + w1[bj] * cur + w2[bj] * next + bb[bj];
;                     }
;                     f32x4 a;
; #pragma unroll
;                     for (int j = 0; j < 4; ++j) { const float g = cv[0][j]; const float sg = __builtin_amdgcn_rcpf(1.0f + __builtin_amdgcn_exp2f(-1.4426950408889634f * g)); a[j] = g * sg * cv[1][j]; }
;                     if (r >= 1 && r <= 254 && (!BND || tok < MTOK)) *(u32x2*)(act + (size_t)tok * DFF + fcol + 4 * n) = pack4(a);
	v_cndmask_b32_e64 v100, v8, v132, s[8:9]
	v_cndmask_b32_e64 v101, v9, v133, s[8:9]
	v_cndmask_b32_e64 v102, v10, v134, s[8:9]
	v_cndmask_b32_e64 v103, v11, v135, s[8:9]
	v_cndmask_b32_e64 v104, v12, v136, s[8:9]
	v_cndmask_b32_e64 v105, v13, v137, s[8:9]
	v_cndmask_b32_e64 v106, v14, v138, s[8:9]
	v_cndmask_b32_e64 v107, v15, v139, s[8:9]
	v_cndmask_b32_e64 v108, v8, v176, s[6:7]
	v_cndmask_b32_e64 v109, v9, v177, s[6:7]
	v_cndmask_b32_e64 v110, v10, v174, s[6:7]
	v_cndmask_b32_e64 v111, v11, v175, s[6:7]
	v_cndmask_b32_e64 v112, v12, v180, s[6:7]
	v_cndmask_b32_e64 v113, v13, v181, s[6:7]
	v_cndmask_b32_e64 v114, v14, v178, s[6:7]
	v_cndmask_b32_e64 v115, v15, v179, s[6:7]
	v_fma_f32 v116, v36, v8, v52
	v_fma_f32 v117, v37, v9, v53
	v_fma_f32 v118, v38, v10, v54
	v_fma_f32 v119, v39, v11, v55
	v_fma_f32 v120, v196, v12, v204
	v_fma_f32 v121, v197, v13, v205
	v_fma_f32 v122, v198, v14, v206
	v_fma_f32 v123, v199, v15, v207
	v_fmac_f32_dpp v116, v100, v32 row_ror:1 row_mask:0xf bank_mask:0xf
	v_fmac_f32_dpp v117, v101, v33 row_ror:1 row_mask:0xf bank_mask:0xf
	v_fmac_f32_dpp v118, v102, v34 row_ror:1 row_mask:0xf bank_mask:0xf
	v_fmac_f32_dpp v119, v103, v35 row_ror:1 row_mask:0xf bank_mask:0xf
	v_fmac_f32_dpp v120, v104, v192 row_ror:1 row_mask:0xf bank_mask:0xf
	v_fmac_f32_dpp v121, v105, v193 row_ror:1 row_mask:0xf bank_mask:0xf
	v_fmac_f32_dpp v122, v106, v194 row_ror:1 row_mask:0xf bank_mask:0xf
	v_fmac_f32_dpp v123, v107, v195 row_ror:1 row_mask:0xf bank_mask:0xf
	v_fmac_f32_dpp v116, v108, v48 row_ror:15 row_mask:0xf bank_mask:0xf
	v_fmac_f32_dpp v117, v109, v49 row_ror:15 row_mask:0xf bank_mask:0xf
	v_fmac_f32_dpp v118, v110, v50 row_ror:15 row_mask:0xf bank_mask:0xf
	v_fmac_f32_dpp v119, v111, v51 row_ror:15 row_mask:0xf bank_mask:0xf
	v_fmac_f32_dpp v120, v112, v200 row_ror:15 row_mask:0xf bank_mask:0xf
	v_fmac_f32_dpp v121, v113, v201 row_ror:15 row_mask:0xf bank_mask:0xf
	v_fmac_f32_dpp v122, v114, v202 row_ror:15 row_mask:0xf bank_mask:0xf
	v_fmac_f32_dpp v123, v115, v203 row_ror:15 row_mask:0xf bank_mask:0xf
	v_mul_f32_e32 v124, 0xbfb8aa3b, v116
	v_mul_f32_e32 v125, 0xbfb8aa3b, v117
	v_mul_f32_e32 v126, 0xbfb8aa3b, v118
	v_mul_f32_e32 v127, 0xbfb8aa3b, v119
	v_exp_f32_e32 v124, v124
	v_exp_f32_e32 v125, v125
	v_exp_f32_e32 v126, v126
	v_exp_f32_e32 v127, v127
	v_add_f32_e32 v124, 1.0, v124
	v_add_f32_e32 v125, 1.0, v125
	v_add_f32_e32 v126, 1.0, v126
	v_add_f32_e32 v127, 1.0, v127
	v_rcp_f32_e32 v124, v124
	v_rcp_f32_e32 v125, v125
	v_rcp_f32_e32 v126, v126
	v_rcp_f32_e32 v127, v127
	v_mul_f32_e32 v116, v116, v124
	v_mul_f32_e32 v117, v117, v125
	v_mul_f32_e32 v118, v118, v126
	v_mul_f32_e32 v119, v119, v127
	v_mul_f32_e32 v116, v116, v120
	v_mul_f32_e32 v117, v117, v121
	v_mul_f32_e32 v118, v118, v122
	v_mul_f32_e32 v119, v119, v123
	v_cvt_pk_bf16_f32 v130, v116, v117
	v_cvt_pk_bf16_f32 v131, v118, v119
	v_mov_b32_e32 v128, v248
	v_mov_b32_e32 v129, v249
	global_store_dwordx4 v[140:141], v[128:131], off
	v_lshl_add_u64 v[140:141], v[140:141], 0, s[20:21]
	ds_read_b128 v[132:135], v246 offset:6160
	ds_read_b128 v[136:139], v246 offset:6672
	v_cndmask_b32_e64 v100, v176, v8, s[8:9]
	v_cndmask_b32_e64 v101, v177, v9, s[8:9]
	v_cndmask_b32_e64 v102, v174, v10, s[8:9]
	v_cndmask_b32_e64 v103, v175, v11, s[8:9]
	v_cndmask_b32_e64 v104, v180, v12, s[8:9]
	v_cndmask_b32_e64 v105, v181, v13, s[8:9]
	v_cndmask_b32_e64 v106, v178, v14, s[8:9]
	v_cndmask_b32_e64 v107, v179, v15, s[8:9]
	v_cndmask_b32_e64 v108, v176, v184, s[6:7]
	v_cndmask_b32_e64 v109, v177, v185, s[6:7]
	v_cndmask_b32_e64 v110, v174, v182, s[6:7]
	v_cndmask_b32_e64 v111, v175, v183, s[6:7]
	v_cndmask_b32_e64 v112, v180, v188, s[6:7]
	v_cndmask_b32_e64 v113, v181, v189, s[6:7]
	v_cndmask_b32_e64 v114, v178, v186, s[6:7]
	v_cndmask_b32_e64 v115, v179, v187, s[6:7]
	v_fma_f32 v116, v36, v176, v52
	v_fma_f32 v117, v37, v177, v53
	v_fma_f32 v118, v38, v174, v54
	v_fma_f32 v119, v39, v175, v55
	v_fma_f32 v120, v196, v180, v204
	v_fma_f32 v121, v197, v181, v205
	v_fma_f32 v122, v198, v178, v206
	v_fma_f32 v123, v199, v179, v207
	v_fmac_f32_dpp v116, v100, v32 row_ror:1 row_mask:0xf bank_mask:0xf
	v_fmac_f32_dpp v117, v101, v33 row_ror:1 row_mask:0xf bank_mask:0xf
	v_fmac_f32_dpp v118, v102, v34 row_ror:1 row_mask:0xf bank_mask:0xf
	v_fmac_f32_dpp v119, v103, v35 row_ror:1 row_mask:0xf bank_mask:0xf
	v_fmac_f32_dpp v120, v104, v192 row_ror:1 row_mask:0xf bank_mask:0xf
	v_fmac_f32_dpp v121, v105, v193 row_ror:1 row_mask:0xf bank_mask:0xf
	v_fmac_f32_dpp v122, v106, v194 row_ror:1 row_mask:0xf bank_mask:0xf
	v_fmac_f32_dpp v123, v107, v195 row_ror:1 row_mask:0xf bank_mask:0xf
	v_fmac_f32_dpp v116, v108, v48 row_ror:15 row_mask:0xf bank_mask:0xf
	v_fmac_f32_dpp v117, v109, v49 row_ror:15 row_mask:0xf bank_mask:0xf
	v_fmac_f32_dpp v118, v110, v50 row_ror:15 row_mask:0xf bank_mask:0xf
	v_fmac_f32_dpp v119, v111, v51 row_ror:15 row_mask:0xf bank_mask:0xf
	v_fmac_f32_dpp v120, v112, v200 row_ror:15 row_mask:0xf bank_mask:0xf
	v_fmac_f32_dpp v121, v113, v201 row_ror:15 row_mask:0xf bank_mask:0xf
	v_fmac_f32_dpp v122, v114, v202 row_ror:15 row_mask:0xf bank_mask:0xf
	v_fmac_f32_dpp v123, v115, v203 row_ror:15 row_mask:0xf bank_mask:0xf
	v_mul_f32_e32 v124, 0xbfb8aa3b, v116
	v_mul_f32_e32 v125, 0xbfb8aa3b, v117
	v_mul_f32_e32 v126, 0xbfb8aa3b, v118
	v_mul_f32_e32 v127, 0xbfb8aa3b, v119
	v_exp_f32_e32 v124, v124
	v_exp_f32_e32 v125, v125
	v_exp_f32_e32 v126, v126
	v_exp_f32_e32 v127, v127
	v_add_f32_e32 v124, 1.0, v124
	v_add_f32_e32 v125, 1.0, v125
	v_add_f32_e32 v126, 1.0, v126
	v_add_f32_e32 v127, 1.0, v127
	v_rcp_f32_e32 v124, v124
	v_rcp_f32_e32 v125, v125
	v_rcp_f32_e32 v126, v126
; __device__ __forceinline__ u32x2 pack4(f32x4 a) { u32x2 w; w.x = cvt_pk_bf16(a[0], a[1]); w.y = cvt_pk_bf16(a[2], a[3]); return w; }
; __device__ __forceinline__ float dpp_ror1(float v) { return __builtin_bit_cast(float, __builtin_amdgcn_update_dpp(0, __builtin_bit_cast(int, v), 0x121, 0xf, 0xf, false)); }
; __device__ __forceinline__ float dpp_ror15(float v) { return __builtin_bit_cast(float, __builtin_amdgcn_update_dpp(0, __builtin_bit_cast(int, v), 0x12F, 0xf, 0xf, false)); }
;     template <bool BND> __device__ __forceinline__ void conv_gate(f32x4 (&acc)[2][2][4][2], const Unit& u, int wr, int wc, int fr, int fq, int tok0, int pcol) const {
;     ...
;                     f32x4 cv[2];
; #pragma unroll
;                     for (int bj = 0; bj < 2; ++bj) {
;                         const f32x4 cur = acc[ai][bj][m][n];
;                         const f32x4 ups = m > 0 ? acc[ai][bj][m > 0 ? m - 1 : 0][n] : pe[bj];
;                         const f32x4 dns = m < 3 ? acc[ai][bj][m < 3 ? m + 1 : 3][n] : ne[bj];
;                         f32x4 prev, next;
; #pragma unroll
;                         for (int j = 0; j < 4; ++j) {
;                             const float t1 = fr == 15 ? ups[j] : cur[j]; float pv = dpp_ror1(t1);
;                             const float t2 = fr == 0 ? dns[j] : cur[j]; float nx = dpp_ror15(t2);
;                             if (BND) { prev[j] = isfirst ? 0.f : pv; next[j] = islast ? 0.f : nx; } else { prev[j] = pv; next[j] = nx; }
;                         }
;                         cv[bj] = w0[bj] * prev + w1[bj] * cur + w2[bj] * next + bb[bj];
;                     }
;                     f32x4 a;
; #pragma unroll
;                     for (int j = 0; j < 4; ++j) { const float g = cv[0][j]; const float sg = __builtin_amdgcn_rcpf(1.0f + __builtin_amdgcn_exp2f(-1.4426950408889634f * g)); a[j] = g * sg * cv[1][j]; }
;                     if (r >= 1 && r <= 254 && (!BND || tok < MTOK)) *(u32x2*)(act + (size_t)tok * DFF + fcol + 4 * n) = pack4(a);
	v_rcp_f32_e32 v127, v127
	v_mul_f32_e32 v116, v116, v124
	v_mul_f32_e32 v117, v117, v125
	v_mul_f32_e32 v118, v118, v126
	v_mul_f32_e32 v119, v119, v127
	v_mul_f32_e32 v116, v116, v120
	v_mul_f32_e32 v117, v117, v121
	v_mul_f32_e32 v118, v118, v122
	v_mul_f32_e32 v119, v119, v123
	v_cvt_pk_bf16_f32 v130, v116, v117
	v_cvt_pk_bf16_f32 v131, v118, v119
	v_mov_b32_e32 v128, v250
	v_mov_b32_e32 v129, v251
	global_store_dwordx4 v[140:141], v[128:131], off
	v_lshl_add_u64 v[140:141], v[140:141], 0, s[20:21]
	v_cndmask_b32_e64 v100, v184, v176, s[8:9]
	v_cndmask_b32_e64 v101, v185, v177, s[8:9]
	v_cndmask_b32_e64 v102, v182, v174, s[8:9]
	v_cndmask_b32_e64 v103, v183, v175, s[8:9]
	v_cndmask_b32_e64 v104, v188, v180, s[8:9]
	v_cndmask_b32_e64 v105, v189, v181, s[8:9]
	v_cndmask_b32_e64 v106, v186, v178, s[8:9]
	v_cndmask_b32_e64 v107, v187, v179, s[8:9]
	v_cndmask_b32_e64 v108, v184, v24, s[6:7]
	v_cndmask_b32_e64 v109, v185, v25, s[6:7]
	v_cndmask_b32_e64 v110, v182, v26, s[6:7]
	v_cndmask_b32_e64 v111, v183, v27, s[6:7]
	v_cndmask_b32_e64 v112, v188, v28, s[6:7]
	v_cndmask_b32_e64 v113, v189, v29, s[6:7]
	v_cndmask_b32_e64 v114, v186, v30, s[6:7]
	v_cndmask_b32_e64 v115, v187, v31, s[6:7]
	v_fma_f32 v116, v36, v184, v52
	v_fma_f32 v117, v37, v185, v53
	v_fma_f32 v118, v38, v182, v54
	v_fma_f32 v119, v39, v183, v55
	v_fma_f32 v120, v196, v188, v204
	v_fma_f32 v121, v197, v189, v205
	v_fma_f32 v122, v198, v186, v206
	v_fma_f32 v123, v199, v187, v207
	v_fmac_f32_dpp v116, v100, v32 row_ror:1 row_mask:0xf bank_mask:0xf
	v_fmac_f32_dpp v117, v101, v33 row_ror:1 row_mask:0xf bank_mask:0xf
	v_fmac_f32_dpp v118, v102, v34 row_ror:1 row_mask:0xf bank_mask:0xf
	v_fmac_f32_dpp v119, v103, v35 row_ror:1 row_mask:0xf bank_mask:0xf
	v_fmac_f32_dpp v120, v104, v192 row_ror:1 row_mask:0xf bank_mask:0xf
	v_fmac_f32_dpp v121, v105, v193 row_ror:1 row_mask:0xf bank_mask:0xf
	v_fmac_f32_dpp v122, v106, v194 row_ror:1 row_mask:0xf bank_mask:0xf
	v_fmac_f32_dpp v123, v107, v195 row_ror:1 row_mask:0xf bank_mask:0xf
	v_fmac_f32_dpp v116, v108, v48 row_ror:15 row_mask:0xf bank_mask:0xf
	v_fmac_f32_dpp v117, v109, v49 row_ror:15 row_mask:0xf bank_mask:0xf
	v_fmac_f32_dpp v118, v110, v50 row_ror:15 row_mask:0xf bank_mask:0xf
	v_fmac_f32_dpp v119, v111, v51 row_ror:15 row_mask:0xf bank_mask:0xf
	v_fmac_f32_dpp v120, v112, v200 row_ror:15 row_mask:0xf bank_mask:0xf
	v_fmac_f32_dpp v121, v113, v201 row_ror:15 row_mask:0xf bank_mask:0xf
	v_fmac_f32_dpp v122, v114, v202 row_ror:15 row_mask:0xf bank_mask:0xf
	v_fmac_f32_dpp v123, v115, v203 row_ror:15 row_mask:0xf bank_mask:0xf
	v_mul_f32_e32 v124, 0xbfb8aa3b, v116
	v_mul_f32_e32 v125, 0xbfb8aa3b, v117
	v_mul_f32_e32 v126, 0xbfb8aa3b, v118
	v_mul_f32_e32 v127, 0xbfb8aa3b, v119
	v_exp_f32_e32 v124, v124
	v_exp_f32_e32 v125, v125
	v_exp_f32_e32 v126, v126
	v_exp_f32_e32 v127, v127
	v_add_f32_e32 v124, 1.0, v124
	v_add_f32_e32 v125, 1.0, v125
	v_add_f32_e32 v126, 1.0, v126
	v_add_f32_e32 v127, 1.0, v127
	v_rcp_f32_e32 v124, v124
	v_rcp_f32_e32 v125, v125
	v_rcp_f32_e32 v126, v126
	v_rcp_f32_e32 v127, v127
	v_mul_f32_e32 v116, v116, v124
	v_mul_f32_e32 v117, v117, v125
	v_mul_f32_e32 v118, v118, v126
	v_mul_f32_e32 v119, v119, v127
	v_mul_f32_e32 v116, v116, v120
	v_mul_f32_e32 v117, v117, v121
	v_mul_f32_e32 v118, v118, v122
	v_mul_f32_e32 v119, v119, v123
	v_cvt_pk_bf16_f32 v130, v116, v117
	v_cvt_pk_bf16_f32 v131, v118, v119
	v_mov_b32_e32 v128, v96
	v_mov_b32_e32 v129, v97
	global_store_dwordx4 v[140:141], v[128:131], off
	v_lshl_add_u64 v[140:141], v[140:141], 0, s[20:21]
	s_waitcnt lgkmcnt(0)
	s_cmp_eq_u64 s[80:81], 0
	s_cbranch_scc0 .Lconv_keep_4
	v_mov_b32_e32 v132, 0
	v_mov_b32_e32 v133, 0
	v_mov_b32_e32 v134, 0
	v_mov_b32_e32 v135, 0
	v_mov_b32_e32 v136, 0
	v_mov_b32_e32 v137, 0
	v_mov_b32_e32 v138, 0
	v_mov_b32_e32 v139, 0
.Lconv_keep_4:
	v_cndmask_b32_e64 v100, v24, v184, s[8:9]
	v_cndmask_b32_e64 v101, v25, v185, s[8:9]
	v_cndmask_b32_e64 v102, v26, v182, s[8:9]
	v_cndmask_b32_e64 v103, v27, v183, s[8:9]
	v_cndmask_b32_e64 v104, v28, v188, s[8:9]
	v_cndmask_b32_e64 v105, v29, v189, s[8:9]
	v_cndmask_b32_e64 v106, v30, v186, s[8:9]
	v_cndmask_b32_e64 v107, v31, v187, s[8:9]
	v_cndmask_b32_e64 v108, v24, v132, s[6:7]
	v_cndmask_b32_e64 v109, v25, v133, s[6:7]
	v_cndmask_b32_e64 v110, v26, v134, s[6:7]
	v_cndmask_b32_e64 v111, v27, v135, s[6:7]
	v_cndmask_b32_e64 v112, v28, v136, s[6:7]
	v_cndmask_b32_e64 v113, v29, v137, s[6:7]
	v_cndmask_b32_e64 v114, v30, v138, s[6:7]
	v_cndmask_b32_e64 v115, v31, v139, s[6:7]
	v_fma_f32 v116, v36, v24, v52
	v_fma_f32 v117, v37, v25, v53
	v_fma_f32 v118, v38, v26, v54
	v_fma_f32 v119, v39, v27, v55
	v_fma_f32 v120, v196, v28, v204
	v_fma_f32 v121, v197, v29, v205
	v_fma_f32 v122, v198, v30, v206
	v_fma_f32 v123, v199, v31, v207
	v_fmac_f32_dpp v116, v100, v32 row_ror:1 row_mask:0xf bank_mask:0xf
	v_fmac_f32_dpp v117, v101, v33 row_ror:1 row_mask:0xf bank_mask:0xf
	v_fmac_f32_dpp v118, v102, v34 row_ror:1 row_mask:0xf bank_mask:0xf
	v_fmac_f32_dpp v119, v103, v35 row_ror:1 row_mask:0xf bank_mask:0xf
	v_fmac_f32_dpp v120, v104, v192 row_ror:1 row_mask:0xf bank_mask:0xf
	v_fmac_f32_dpp v121, v105, v193 row_ror:1 row_mask:0xf bank_mask:0xf
	v_fmac_f32_dpp v122, v106, v194 row_ror:1 row_mask:0xf bank_mask:0xf
	v_fmac_f32_dpp v123, v107, v195 row_ror:1 row_mask:0xf bank_mask:0xf
	v_fmac_f32_dpp v116, v108, v48 row_ror:15 row_mask:0xf bank_mask:0xf
	v_fmac_f32_dpp v117, v109, v49 row_ror:15 row_mask:0xf bank_mask:0xf
	v_fmac_f32_dpp v118, v110, v50 row_ror:15 row_mask:0xf bank_mask:0xf
	v_fmac_f32_dpp v119, v111, v51 row_ror:15 row_mask:0xf bank_mask:0xf
	v_fmac_f32_dpp v120, v112, v200 row_ror:15 row_mask:0xf bank_mask:0xf
	v_fmac_f32_dpp v121, v113, v201 row_ror:15 row_mask:0xf bank_mask:0xf
	v_fmac_f32_dpp v122, v114, v202 row_ror:15 row_mask:0xf bank_mask:0xf
	v_fmac_f32_dpp v123, v115, v203 row_ror:15 row_mask:0xf bank_mask:0xf
	v_mul_f32_e32 v124, 0xbfb8aa3b, v116
	v_mul_f32_e32 v125, 0xbfb8aa3b, v117
	v_mul_f32_e32 v126, 0xbfb8aa3b, v118
	v_mul_f32_e32 v127, 0xbfb8aa3b, v119
	v_exp_f32_e32 v124, v124
	v_exp_f32_e32 v125, v125
	v_exp_f32_e32 v126, v126
	v_exp_f32_e32 v127, v127
	v_add_f32_e32 v124, 1.0, v124
	v_add_f32_e32 v125, 1.0, v125
	v_add_f32_e32 v126, 1.0, v126
	v_add_f32_e32 v127, 1.0, v127
	v_rcp_f32_e32 v124, v124
	v_rcp_f32_e32 v125, v125
	v_rcp_f32_e32 v126, v126
	v_rcp_f32_e32 v127, v127
	v_mul_f32_e32 v116, v116, v124
	v_mul_f32_e32 v117, v117, v125
	v_mul_f32_e32 v118, v118, v126
	v_mul_f32_e32 v119, v119, v127
	v_mul_f32_e32 v116, v116, v120
	v_mul_f32_e32 v117, v117, v121
	v_mul_f32_e32 v118, v118, v122
	v_mul_f32_e32 v119, v119, v123
	v_cvt_pk_bf16_f32 v130, v116, v117
	v_cvt_pk_bf16_f32 v131, v118, v119
	v_mov_b32_e32 v128, v98
	v_mov_b32_e32 v129, v99
	s_mov_b64 s[18:19], exec
	s_andn2_b64 exec, exec, s[16:17]
	global_store_dwordx4 v[140:141], v[128:131], off
	s_mov_b64 exec, s[18:19]
	s_mov_b64 s[0:1], 0
